# chain: each wave's 4 wave-private VT LDS-DMA pieces for the next step issued at the end of the previous step body (before the rendezvous), step top issues only PD pieces; top wait vmcnt(20)
# speedup vs baseline: 1.0155x; 1.0155x over previous
; #define LAS __attribute__((address_space(3)))
; #define RD_QD(dst, s0) _Pragma("unroll") for (int s_ = 0; s_ < 4; ++s_) { dst[s_] = *(const LAS bf16x8*)(B + CH_QD + i0 * 256 + (((2 * ((s0) + s_) + hi) ^ (i0 & 15)) << 4)); \
;                 dst[4 + s_] = *(const LAS bf16x8*)(B + CH_QD + i1 * 256 + (((2 * ((s0) + s_) + hi) ^ (i1 & 15)) << 4)); }
; #define DECAY(db_) do { f32x4 dc_[4]; _Pragma("unroll") for (int a4_ = 0; a4_ < 4; ++a4_) dc_[a4_] = *(const LAS f32x4*)(B + CH_DEC + ((db_) * 32 + 8 * a4_ + 4 * hi) * 4); \
;                 _Pragma("unroll") for (int a4_ = 0; a4_ < 4; ++a4_) _Pragma("unroll") for (int b4_ = 0; b4_ < 4; ++b4_) T[db_][a4_ * 4 + b4_] *= dc_[a4_][b4_]; } while (0)
; DI void phase_gla_chain(const Params& P, int l, int task0, int ntask_stride, LAS unsigned char* lds) {
;     ...
;         const int dir = task & 1, h = (task >> 1) & 3, sq = task >> 3;
;         f32x16 T[4]; for (int d = 0; d < 4; ++d) for (int x = 0; x < 16; ++x) T[d][x] = 0.f;
;     ...
;             const int i0 = r32, i1 = 32 + r32; const int vv = wid * 32 + r32;
;             bf16x8 fa[8], fb[8], vf[4];
;             f32x16 o[2]; for (int x = 0; x < 16; ++x) { o[0][x] = 0.f; o[1][x] = 0.f; }
;     ...
;             RD_QD(fa, 0);
; #pragma unroll
;             for (int ks = 0; ks < 4; ++ks) vf[ks] = *(const LAS bf16x8*)(B + CH_VT + vv * 128 + (((2 * ks + hi) ^ ((vv >> 1) & 7)) << 4));
;             __builtin_amdgcn_sched_barrier(0);
;             RD_QD(fb, 4);
;             __builtin_amdgcn_sched_barrier(0);
;             MM_QD(fa, 0);
;             DECAY(0); DECAY(1);
;             __builtin_amdgcn_sched_barrier(0);
; #pragma unroll
;             for (int ks = 0; ks < 4; ++ks) { fa[ks] = *(const LAS bf16x8*)(B + CH_AM + i0 * 128 + (((2 * ks + hi) ^ ((i0 >> 1) & 7)) << 4)); fa[4 + ks] = *(const LAS bf16x8*)(B + CH_AM + i1 * 128 + (((2 * ks + hi) ^ ((i1 >> 1) & 7)) << 4)); }
;             __builtin_amdgcn_sched_barrier(0);
;             MM_QD(fb, 4);
;             DECAY(2); DECAY(3);
;             __builtin_amdgcn_sched_barrier(0);
.LBB0_408:
	ds_read_b128 v[2:5], v176
	ds_read_b128 v[6:9], v177
	ds_read_b128 v[10:13], v178
	ds_read_b128 v[14:17], v179
	ds_read_b128 v[18:21], v180
	ds_read_b128 v[22:25], v181
	v_add_u32_e32 v26, v206, v160
	v_add_u32_e32 v30, v147, v160
	ds_read_b128 v[26:29], v26
	ds_read_b128 v[34:37], v30
	v_add_u32_e32 v30, v174, v162
	v_add_u32_e32 v31, v174, v164
	ds_read_b128 v[110:113], v30 offset:40960
	ds_read_b128 v[106:109], v31 offset:40960
	v_add_u32_e32 v30, v174, v165
	v_add_u32_e32 v31, v174, v166
	ds_read_b128 v[102:105], v30 offset:40960
	ds_read_b128 v[98:101], v31 offset:40960
	s_ashr_i32 s21, s20, 31
	s_lshl_b32 s8, s88, 9
	s_lshl_b64 s[20:21], s[20:21], 12
	v_lshl_add_u64 v[158:159], v[154:155], 0, s[8:9]
	v_add_u32_e32 v30, v206, v167
	v_add_u32_e32 v31, v147, v167
	ds_read_b128 v[38:41], v30
	ds_read_b128 v[42:45], v31
	v_add_u32_e32 v30, v206, v168
	v_add_u32_e32 v31, v147, v168
	ds_read_b128 v[46:49], v30
	ds_read_b128 v[50:53], v31
	v_add_u32_e32 v30, v206, v169
	v_add_u32_e32 v31, v147, v169
	ds_read_b128 v[54:57], v30
	ds_read_b128 v[58:61], v31
	v_add_u32_e32 v30, v206, v170
	v_add_u32_e32 v31, v147, v170
	ds_read_b128 v[62:65], v30
	ds_read_b128 v[114:117], v31
	v_mov_b64_e32 v[120:121], s[6:7]
	v_mov_b64_e32 v[118:119], s[4:5]
	v_add_u32_e32 v207, 0, v146
	s_waitcnt lgkmcnt(0)
	v_mfma_f32_32x32x16_bf16 v[82:97], v[2:5], v[118:121], 0
	v_mfma_f32_32x32x16_bf16 v[66:81], v[6:9], v[118:121], 0
	v_mfma_f32_32x32x16_bf16 v[82:97], v[10:13], v[118:121], v[82:97]
	v_add_u32_e32 v10, 0x12000, v207
	ds_read_b128 v[2:5], v10 offset:64
	ds_read_b128 v[6:9], v10 offset:96
	s_waitcnt lgkmcnt(0)
	v_mul_f32_e64 v12, v4, 0
	v_mul_f32_e64 v13, v5, 0
	v_mfma_f32_32x32x16_bf16 v[66:81], v[14:17], v[118:121], v[66:81]
	v_mul_f32_e64 v16, v8, 0
	v_mul_f32_e64 v17, v9, 0
	v_mul_f32_e64 v14, v6, 0
	v_mul_f32_e64 v15, v7, 0
	v_mfma_f32_32x32x16_bf16 v[82:97], v[18:21], v[118:121], v[82:97]
	ds_read_b128 v[18:21], v10 offset:32
	ds_read_b128 v[30:33], v10
	v_mul_f32_e64 v10, v2, 0
	v_mul_f32_e64 v11, v3, 0
	v_add_u32_e32 v2, 0x12080, v207
	s_waitcnt lgkmcnt(0)
	v_pk_mul_f32 v[8:9], v[20:21], 0 op_sel_hi:[1,0]
	v_pk_mul_f32 v[6:7], v[18:19], 0 op_sel_hi:[1,0]
	v_pk_mul_f32 v[4:5], v[32:33], 0 op_sel_hi:[1,0]
	v_mfma_f32_32x32x16_bf16 v[66:81], v[22:25], v[118:121], v[66:81]
	ds_read_b128 v[18:21], v2 offset:64
	ds_read_b128 v[22:25], v2 offset:96
	ds_read_b128 v[122:125], v2
	ds_read_b128 v[126:129], v2 offset:32
	v_mul_f32_e64 v2, v30, 0
	v_mul_f32_e64 v3, v31, 0
	s_waitcnt lgkmcnt(0)
	v_pk_mul_f32 v[32:33], v[24:25], 0 op_sel_hi:[1,0]
	v_pk_mul_f32 v[30:31], v[22:23], 0 op_sel_hi:[1,0]
	v_pk_mul_f32 v[24:25], v[128:129], 0 op_sel_hi:[1,0]
	v_pk_mul_f32 v[22:23], v[126:127], 0 op_sel_hi:[1,0]
	v_mfma_f32_32x32x16_bf16 v[82:97], v[26:29], v[118:121], v[82:97]
	v_mul_f32_e64 v28, v20, 0
	v_mul_f32_e64 v29, v21, 0
	v_mul_f32_e64 v20, v124, 0
	v_mul_f32_e64 v21, v125, 0
	v_mul_f32_e64 v26, v18, 0
	v_mul_f32_e64 v27, v19, 0
	v_pk_mul_f32 v[18:19], v[122:123], 0 op_sel_hi:[1,0]
	v_mfma_f32_32x32x16_bf16 v[66:81], v[34:37], v[118:121], v[66:81]
	v_add_u32_e32 v232, v171, v162
	v_add_u32_e32 v34, v172, v162
	ds_read_b128 v[122:125], v232 offset:16384
	ds_read_b128 v[126:129], v34 offset:16384
	v_add_u32_e32 v233, v171, v164
	v_add_u32_e32 v34, v172, v164
	ds_read_b128 v[130:133], v233 offset:16384
	ds_read_b128 v[182:185], v34 offset:16384
	v_add_u32_e32 v234, v171, v165
	v_add_u32_e32 v34, v172, v165
	v_add_u32_e32 v235, v171, v166
	ds_read_b128 v[186:189], v234 offset:16384
	ds_read_b128 v[190:193], v34 offset:16384
	v_add_u32_e32 v34, v172, v166
	ds_read_b128 v[194:197], v235 offset:16384
	ds_read_b128 v[198:201], v34 offset:16384
	v_mfma_f32_32x32x16_bf16 v[82:97], v[38:41], v[118:121], v[82:97]
	v_mfma_f32_32x32x16_bf16 v[66:81], v[42:45], v[118:121], v[66:81]
	v_add_u32_e32 v42, 0x12100, v207
	ds_read_b128 v[34:37], v42 offset:64
	ds_read_b128 v[38:41], v42 offset:96
	s_waitcnt lgkmcnt(0)
	v_mul_f32_e64 v44, v36, 0
	v_mul_f32_e64 v45, v37, 0
	v_mfma_f32_32x32x16_bf16 v[82:97], v[46:49], v[118:121], v[82:97]
	v_mul_f32_e64 v48, v40, 0
	v_mul_f32_e64 v49, v41, 0
	v_mul_f32_e64 v46, v38, 0
	v_mul_f32_e64 v47, v39, 0
	v_mfma_f32_32x32x16_bf16 v[66:81], v[50:53], v[118:121], v[66:81]
	v_mfma_f32_32x32x16_bf16 v[82:97], v[54:57], v[118:121], v[82:97]
	ds_read_b128 v[50:53], v42 offset:32
	ds_read_b128 v[54:57], v42
	v_mul_f32_e64 v42, v34, 0
	v_mul_f32_e64 v43, v35, 0
	v_add_u32_e32 v34, 0x12180, v207
	s_waitcnt lgkmcnt(0)
	v_pk_mul_f32 v[40:41], v[52:53], 0 op_sel_hi:[1,0]
	v_pk_mul_f32 v[38:39], v[50:51], 0 op_sel_hi:[1,0]
	v_pk_mul_f32 v[36:37], v[56:57], 0 op_sel_hi:[1,0]
	v_mfma_f32_32x32x16_bf16 v[66:81], v[58:61], v[118:121], v[66:81]
	ds_read_b128 v[50:53], v34 offset:64
	ds_read_b128 v[58:61], v34 offset:96
	ds_read_b128 v[208:211], v34
	ds_read_b128 v[212:215], v34 offset:32
	v_mul_f32_e64 v34, v54, 0
	v_mul_f32_e64 v35, v55, 0
	s_waitcnt lgkmcnt(0)
; DI int crow(int r, int hi) { return (r & 3) + 8 * (r >> 2) + 4 * hi; }
; DI unsigned pkbf(float a, float b) { f32x2 v = {a, b}; bfx2 r = __builtin_convertvector(v, bfx2); return __builtin_bit_cast(unsigned, r); }
; #define RD_KT(dst, db0) _Pragma("unroll") for (int q_ = 0; q_ < 2; ++q_) { const int d_ = ((db0) + q_) * 32 + r32; \
;                 _Pragma("unroll") for (int ks_ = 0; ks_ < 4; ++ks_) dst[q_ * 4 + ks_] = *(const LAS bf16x8*)(B + CH_KT + d_ * 128 + (((2 * ks_ + hi) ^ ((d_ >> 1) & 7)) << 4)); }
; #define MM_KT(src, db0) _Pragma("unroll") for (int q_ = 0; q_ < 2; ++q_) { \
;                 _Pragma("unroll") for (int ks_ = 0; ks_ < 4; ++ks_) T[(db0) + q_] = __builtin_amdgcn_mfma_f32_32x32x16_bf16(src[q_ * 4 + ks_], vf[ks_], T[(db0) + q_], 0, 0, 0); }
; DI void phase_gla_chain(const Params& P, int l, int task0, int ntask_stride, LAS unsigned char* lds) {
;     ...
;             RD_KT(fb, 0);
;             __builtin_amdgcn_sched_barrier(0);
; #pragma unroll
;             for (int ks = 0; ks < 4; ++ks) { o[0] = __builtin_amdgcn_mfma_f32_32x32x16_bf16(fa[ks], vf[ks], o[0], 0, 0, 0); o[1] = __builtin_amdgcn_mfma_f32_32x32x16_bf16(fa[4 + ks], vf[ks], o[1], 0, 0, 0); }
;             __builtin_amdgcn_sched_barrier(0);
;             RD_KT(fa, 2);
;             __builtin_amdgcn_sched_barrier(0);
;             MM_KT(fb, 0);
;             __builtin_amdgcn_sched_barrier(0);
;             MM_KT(fa, 2);
;     ...
;             { const int cs = dir ? 63 - n : n; const size_t tokb = (size_t)sq * SEQL + cs * 64; const int odd = lane & 1;
;               bf16_t* ob = OFB + (size_t)dir * MTOK * 1024 + h * 256 + wid * 32 + (r32 & ~1);
; #pragma unroll
;               for (int ib = 0; ib < 2; ++ib)
; #pragma unroll
;                   for (int x = 0; x < 16; x += 2) { float ea_ = o[ib][x], eb_ = o[ib][x + 1]; asm volatile("" : "+v"(ea_), "+v"(eb_)); const float mine = odd ? eb_ : ea_, give = odd ? ea_ : eb_;
;                       const float got = __int_as_float(__builtin_amdgcn_update_dpp(0, __float_as_int(give), 0xB1, 0xF, 0xF, true));
;                       const unsigned w = odd ? pkbf(got, mine) : pkbf(mine, got);
;                       *(unsigned*)(ob + (tokb + ib * 32 + crow(x + odd, hi)) * 1024) = w; } }
	v_pk_mul_f32 v[56:57], v[214:215], 0 op_sel_hi:[1,0]
	v_pk_mul_f32 v[54:55], v[212:213], 0 op_sel_hi:[1,0]
	v_mfma_f32_32x32x16_bf16 v[82:97], v[62:65], v[118:121], v[82:97]
	v_mul_f32_e64 v64, v60, 0
	v_mul_f32_e64 v65, v61, 0
	v_mul_f32_e64 v60, v52, 0
	v_mul_f32_e64 v61, v53, 0
	v_mul_f32_e64 v52, v210, 0
	v_mul_f32_e64 v53, v211, 0
	v_pk_mul_f32 v[62:63], v[58:59], 0 op_sel_hi:[1,0]
	v_pk_mul_f32 v[58:59], v[50:51], 0 op_sel_hi:[1,0]
	v_pk_mul_f32 v[50:51], v[208:209], 0 op_sel_hi:[1,0]
	v_mfma_f32_32x32x16_bf16 v[66:81], v[114:117], v[118:121], v[66:81]
	ds_read_b128 v[114:117], v232 offset:24576
	ds_read_b128 v[118:121], v232 offset:28672
	ds_read_b128 v[208:211], v233 offset:24576
	ds_read_b128 v[212:215], v233 offset:28672
	ds_read_b128 v[216:219], v234 offset:24576
	ds_read_b128 v[220:223], v234 offset:28672
	ds_read_b128 v[224:227], v235 offset:24576
	ds_read_b128 v[228:231], v235 offset:28672
	v_mfma_f32_32x32x16_bf16 v[82:97], v[122:125], v[110:113], v[82:97]
	v_mfma_f32_32x32x16_bf16 v[66:81], v[126:129], v[110:113], v[66:81]
	v_mfma_f32_32x32x16_bf16 v[82:97], v[130:133], v[106:109], v[82:97]
	v_mfma_f32_32x32x16_bf16 v[66:81], v[182:185], v[106:109], v[66:81]
	v_mfma_f32_32x32x16_bf16 v[82:97], v[186:189], v[102:105], v[82:97]
	v_mfma_f32_32x32x16_bf16 v[66:81], v[190:193], v[102:105], v[66:81]
	v_mfma_f32_32x32x16_bf16 v[82:97], v[194:197], v[98:101], v[82:97]
	v_mfma_f32_32x32x16_bf16 v[66:81], v[198:201], v[98:101], v[66:81]
	ds_read_b128 v[122:125], v232 offset:32768
	ds_read_b128 v[126:129], v232 offset:36864
	ds_read_b128 v[130:133], v233 offset:32768
	ds_read_b128 v[182:185], v233 offset:36864
	ds_read_b128 v[186:189], v234 offset:32768
	ds_read_b128 v[190:193], v234 offset:36864
	ds_read_b128 v[194:197], v235 offset:32768
	ds_read_b128 v[198:201], v235 offset:36864
	s_waitcnt lgkmcnt(0)
	v_mfma_f32_32x32x16_bf16 v[2:17], v[114:117], v[110:113], v[2:17]
	v_mfma_f32_32x32x16_bf16 v[18:33], v[118:121], v[110:113], v[18:33]
	v_mfma_f32_32x32x16_bf16 v[2:17], v[208:211], v[106:109], v[2:17]
	v_mfma_f32_32x32x16_bf16 v[18:33], v[212:215], v[106:109], v[18:33]
	v_mfma_f32_32x32x16_bf16 v[2:17], v[216:219], v[102:105], v[2:17]
	v_mfma_f32_32x32x16_bf16 v[18:33], v[220:223], v[102:105], v[18:33]
	v_mfma_f32_32x32x16_bf16 v[2:17], v[224:227], v[98:101], v[2:17]
	v_mfma_f32_32x32x16_bf16 v[18:33], v[228:231], v[98:101], v[18:33]
	s_or_b64 s[22:23], s[20:21], s[12:13]
	v_cndmask_b32_e64 v114, v82, v83, s[0:1]
	s_or_b32 s8, s22, 32
	v_mfma_f32_32x32x16_bf16 v[34:49], v[122:125], v[110:113], v[34:49]
	v_mov_b32_dpp v114, v114 quad_perm:[1,0,3,2] row_mask:0xf bank_mask:0xf bound_ctrl:1
	v_cndmask_b32_e64 v83, v83, v114, s[0:1]
	v_cndmask_b32_e64 v82, v114, v82, s[0:1]
	v_cvt_pk_bf16_f32 v114, v82, v83
	v_mov_b32_e32 v83, s23
	v_or_b32_e32 v82, s22, v136
	v_lshlrev_b64 v[82:83], 11, v[82:83]
	v_lshl_add_u64 v[82:83], v[158:159], 0, v[82:83]
	global_store_dword v[82:83], v114, off
	v_mov_b32_e32 v82, v85
	v_mfma_f32_32x32x16_bf16 v[50:65], v[126:129], v[110:113], v[50:65]
	v_cndmask_b32_e64 v83, v84, v82, s[0:1]
	s_mov_b32 s90, 2
	s_nop 0
	v_mov_b32_dpp v83, v83 quad_perm:[1,0,3,2] row_mask:0xf bank_mask:0xf bound_ctrl:1
	v_cndmask_b32_e64 v82, v82, v83, s[0:1]
	v_cndmask_b32_e64 v83, v83, v84, s[0:1]
	v_cvt_pk_bf16_f32 v84, v83, v82
	v_mov_b32_e32 v83, s23
	v_or_b32_e32 v82, s22, v138
	v_lshlrev_b64 v[82:83], 11, v[82:83]
	v_lshl_add_u64 v[82:83], v[158:159], 0, v[82:83]
	global_store_dword v[82:83], v84, off
	v_mov_b32_e32 v82, v86
	v_mfma_f32_32x32x16_bf16 v[34:49], v[130:133], v[106:109], v[34:49]
	v_cndmask_b32_e64 v83, v82, v87, s[0:1]
	s_nop 1
	v_mov_b32_dpp v83, v83 quad_perm:[1,0,3,2] row_mask:0xf bank_mask:0xf bound_ctrl:1
	v_cndmask_b32_e64 v84, v87, v83, s[0:1]
	v_cndmask_b32_e64 v82, v83, v82, s[0:1]
	v_cvt_pk_bf16_f32 v84, v82, v84
	v_mov_b32_e32 v83, s23
	v_or_b32_e32 v82, s22, v140
	v_lshlrev_b64 v[82:83], 11, v[82:83]
	v_lshl_add_u64 v[82:83], v[158:159], 0, v[82:83]
	global_store_dword v[82:83], v84, off
	v_mov_b32_e32 v82, v88
	v_mfma_f32_32x32x16_bf16 v[50:65], v[182:185], v[106:109], v[50:65]
	v_cndmask_b32_e64 v83, v82, v89, s[0:1]
	s_nop 1
	v_mov_b32_dpp v83, v83 quad_perm:[1,0,3,2] row_mask:0xf bank_mask:0xf bound_ctrl:1
	v_cndmask_b32_e64 v84, v89, v83, s[0:1]
	v_cndmask_b32_e64 v82, v83, v82, s[0:1]
	v_cvt_pk_bf16_f32 v84, v82, v84
	v_mov_b32_e32 v83, s23
	v_or_b32_e32 v82, s22, v142
	v_lshlrev_b64 v[82:83], 11, v[82:83]
	v_lshl_add_u64 v[82:83], v[158:159], 0, v[82:83]
	global_store_dword v[82:83], v84, off
	v_mov_b32_e32 v82, v91
	v_mfma_f32_32x32x16_bf16 v[34:49], v[186:189], v[102:105], v[34:49]
	v_cndmask_b32_e64 v83, v90, v82, s[0:1]
	s_nop 1
	v_mov_b32_dpp v83, v83 quad_perm:[1,0,3,2] row_mask:0xf bank_mask:0xf bound_ctrl:1
	v_cndmask_b32_e64 v82, v82, v83, s[0:1]
	v_cndmask_b32_e64 v83, v83, v90, s[0:1]
	v_cvt_pk_bf16_f32 v84, v83, v82
	v_mov_b32_e32 v83, s23
	v_or_b32_e32 v82, s22, v144
	v_lshlrev_b64 v[82:83], 11, v[82:83]
	v_lshl_add_u64 v[82:83], v[158:159], 0, v[82:83]
	global_store_dword v[82:83], v84, off
	v_mov_b32_e32 v82, v92
	v_mfma_f32_32x32x16_bf16 v[50:65], v[190:193], v[102:105], v[50:65]
	v_cndmask_b32_e64 v83, v82, v93, s[0:1]
	s_nop 1
	v_mov_b32_dpp v83, v83 quad_perm:[1,0,3,2] row_mask:0xf bank_mask:0xf bound_ctrl:1
	v_cndmask_b32_e64 v84, v93, v83, s[0:1]
	v_cndmask_b32_e64 v82, v83, v82, s[0:1]
	v_cvt_pk_bf16_f32 v84, v82, v84
	v_mov_b32_e32 v83, s23
	v_or_b32_e32 v82, s22, v148
	v_lshlrev_b64 v[82:83], 11, v[82:83]
	v_lshl_add_u64 v[82:83], v[158:159], 0, v[82:83]
	global_store_dword v[82:83], v84, off
	v_mov_b32_e32 v82, v94
	v_mfma_f32_32x32x16_bf16 v[34:49], v[194:197], v[98:101], v[34:49]
; DI int crow(int r, int hi) { return (r & 3) + 8 * (r >> 2) + 4 * hi; }
; DI unsigned pkbf(float a, float b) { f32x2 v = {a, b}; bfx2 r = __builtin_convertvector(v, bfx2); return __builtin_bit_cast(unsigned, r); }
; DI void phase_gla_chain(const Params& P, int l, int task0, int ntask_stride, LAS unsigned char* lds) {
;     ...
;             { const int cs = dir ? 63 - n : n; const size_t tokb = (size_t)sq * SEQL + cs * 64; const int odd = lane & 1;
;               bf16_t* ob = OFB + (size_t)dir * MTOK * 1024 + h * 256 + wid * 32 + (r32 & ~1);
; #pragma unroll
;               for (int ib = 0; ib < 2; ++ib)
; #pragma unroll
;                   for (int x = 0; x < 16; x += 2) { float ea_ = o[ib][x], eb_ = o[ib][x + 1]; asm volatile("" : "+v"(ea_), "+v"(eb_)); const float mine = odd ? eb_ : ea_, give = odd ? ea_ : eb_;
;                       const float got = __int_as_float(__builtin_amdgcn_update_dpp(0, __float_as_int(give), 0xB1, 0xF, 0xF, true));
;                       const unsigned w = odd ? pkbf(got, mine) : pkbf(mine, got);
;                       *(unsigned*)(ob + (tokb + ib * 32 + crow(x + odd, hi)) * 1024) = w; } }
	v_cndmask_b32_e64 v83, v82, v95, s[0:1]
	s_nop 1
	v_mov_b32_dpp v83, v83 quad_perm:[1,0,3,2] row_mask:0xf bank_mask:0xf bound_ctrl:1
	v_cndmask_b32_e64 v84, v95, v83, s[0:1]
	v_cndmask_b32_e64 v82, v83, v82, s[0:1]
	v_cvt_pk_bf16_f32 v84, v82, v84
	v_mov_b32_e32 v83, s23
	v_or_b32_e32 v82, s22, v150
	v_lshlrev_b64 v[82:83], 11, v[82:83]
	v_lshl_add_u64 v[82:83], v[158:159], 0, v[82:83]
	global_store_dword v[82:83], v84, off
	v_mov_b32_e32 v82, v97
	v_mfma_f32_32x32x16_bf16 v[50:65], v[198:201], v[98:101], v[50:65]
	v_cndmask_b32_e64 v83, v96, v82, s[0:1]
	s_nop 1
	v_mov_b32_dpp v83, v83 quad_perm:[1,0,3,2] row_mask:0xf bank_mask:0xf bound_ctrl:1
	v_cndmask_b32_e64 v82, v82, v83, s[0:1]
	v_cndmask_b32_e64 v83, v83, v96, s[0:1]
	v_cvt_pk_bf16_f32 v84, v83, v82
	v_mov_b32_e32 v83, s23
	v_or_b32_e32 v82, s22, v152
	v_lshlrev_b64 v[82:83], 11, v[82:83]
	v_lshl_add_u64 v[82:83], v[158:159], 0, v[82:83]
	global_store_dword v[82:83], v84, off
	s_nop 0
	v_cndmask_b32_e64 v82, v66, v67, s[0:1]
	s_nop 1
	v_mov_b32_dpp v82, v82 quad_perm:[1,0,3,2] row_mask:0xf bank_mask:0xf bound_ctrl:1
	v_cndmask_b32_e64 v67, v67, v82, s[0:1]
	v_cndmask_b32_e64 v66, v82, v66, s[0:1]
	v_cvt_pk_bf16_f32 v82, v66, v67
	v_mov_b32_e32 v67, s23
	v_or_b32_e32 v66, s8, v136
	v_lshlrev_b64 v[66:67], 11, v[66:67]
	v_lshl_add_u64 v[66:67], v[158:159], 0, v[66:67]
	global_store_dword v[66:67], v82, off
	v_mov_b32_e32 v66, v68
	s_nop 0
	v_cndmask_b32_e64 v67, v66, v69, s[0:1]
	s_nop 1
	v_mov_b32_dpp v67, v67 quad_perm:[1,0,3,2] row_mask:0xf bank_mask:0xf bound_ctrl:1
	v_cndmask_b32_e64 v68, v69, v67, s[0:1]
	v_cndmask_b32_e64 v66, v67, v66, s[0:1]
	v_cvt_pk_bf16_f32 v68, v66, v68
	v_mov_b32_e32 v67, s23
	v_or_b32_e32 v66, s8, v138
	v_lshlrev_b64 v[66:67], 11, v[66:67]
	v_lshl_add_u64 v[66:67], v[158:159], 0, v[66:67]
	global_store_dword v[66:67], v68, off
	v_mov_b32_e32 v66, v71
	s_nop 0
	v_cndmask_b32_e64 v67, v70, v66, s[0:1]
	s_nop 1
	v_mov_b32_dpp v67, v67 quad_perm:[1,0,3,2] row_mask:0xf bank_mask:0xf bound_ctrl:1
	v_cndmask_b32_e64 v66, v66, v67, s[0:1]
	v_cndmask_b32_e64 v67, v67, v70, s[0:1]
	v_cvt_pk_bf16_f32 v68, v67, v66
	v_mov_b32_e32 v67, s23
	v_or_b32_e32 v66, s8, v140
	v_lshlrev_b64 v[66:67], 11, v[66:67]
	v_lshl_add_u64 v[66:67], v[158:159], 0, v[66:67]
	global_store_dword v[66:67], v68, off
	v_mov_b32_e32 v66, v73
	s_nop 0
	v_cndmask_b32_e64 v67, v72, v66, s[0:1]
	s_nop 1
	v_mov_b32_dpp v67, v67 quad_perm:[1,0,3,2] row_mask:0xf bank_mask:0xf bound_ctrl:1
	v_cndmask_b32_e64 v66, v66, v67, s[0:1]
	v_cndmask_b32_e64 v67, v67, v72, s[0:1]
	v_cvt_pk_bf16_f32 v68, v67, v66
	v_mov_b32_e32 v67, s23
	v_or_b32_e32 v66, s8, v142
	v_lshlrev_b64 v[66:67], 11, v[66:67]
	v_lshl_add_u64 v[66:67], v[158:159], 0, v[66:67]
	global_store_dword v[66:67], v68, off
	v_mov_b32_e32 v66, v74
	s_nop 0
	v_cndmask_b32_e64 v67, v66, v75, s[0:1]
	s_nop 1
	v_mov_b32_dpp v67, v67 quad_perm:[1,0,3,2] row_mask:0xf bank_mask:0xf bound_ctrl:1
	v_cndmask_b32_e64 v68, v75, v67, s[0:1]
	v_cndmask_b32_e64 v66, v67, v66, s[0:1]
	v_cvt_pk_bf16_f32 v68, v66, v68
	v_mov_b32_e32 v67, s23
	v_or_b32_e32 v66, s8, v144
	v_lshlrev_b64 v[66:67], 11, v[66:67]
	v_lshl_add_u64 v[66:67], v[158:159], 0, v[66:67]
	global_store_dword v[66:67], v68, off
	v_mov_b32_e32 v66, v77
	s_nop 0
	v_cndmask_b32_e64 v67, v76, v66, s[0:1]
	s_nop 1
	v_mov_b32_dpp v67, v67 quad_perm:[1,0,3,2] row_mask:0xf bank_mask:0xf bound_ctrl:1
	v_cndmask_b32_e64 v66, v66, v67, s[0:1]
	v_cndmask_b32_e64 v67, v67, v76, s[0:1]
	v_cvt_pk_bf16_f32 v68, v67, v66
	v_mov_b32_e32 v67, s23
	v_or_b32_e32 v66, s8, v148
	v_lshlrev_b64 v[66:67], 11, v[66:67]
	v_lshl_add_u64 v[66:67], v[158:159], 0, v[66:67]
	global_store_dword v[66:67], v68, off
	v_mov_b32_e32 v66, v79
	s_nop 0
	v_cndmask_b32_e64 v67, v78, v66, s[0:1]
	s_nop 1
	v_mov_b32_dpp v67, v67 quad_perm:[1,0,3,2] row_mask:0xf bank_mask:0xf bound_ctrl:1
	v_cndmask_b32_e64 v66, v66, v67, s[0:1]
	v_cndmask_b32_e64 v67, v67, v78, s[0:1]
	v_cvt_pk_bf16_f32 v68, v67, v66
	v_mov_b32_e32 v67, s23
	v_or_b32_e32 v66, s8, v150
	v_lshlrev_b64 v[66:67], 11, v[66:67]
	v_lshl_add_u64 v[66:67], v[158:159], 0, v[66:67]
	global_store_dword v[66:67], v68, off
	v_mov_b32_e32 v66, v80
	s_nop 0
	v_cndmask_b32_e64 v67, v66, v81, s[0:1]
	s_nop 1
	v_mov_b32_dpp v67, v67 quad_perm:[1,0,3,2] row_mask:0xf bank_mask:0xf bound_ctrl:1
	v_cndmask_b32_e64 v68, v81, v67, s[0:1]
	v_cndmask_b32_e64 v66, v67, v66, s[0:1]
	v_cvt_pk_bf16_f32 v68, v66, v68
	v_mov_b32_e32 v67, s23
	v_or_b32_e32 v66, s8, v152
	v_lshlrev_b64 v[66:67], 11, v[66:67]
	v_lshl_add_u64 v[66:67], v[158:159], 0, v[66:67]
	s_mov_b32 s8, 61
	global_store_dword v[66:67], v68, off
	s_cmp_lt_i32 s8, 0
	s_cbranch_scc1 .Lvt_p_0
	s_and_b64 s[66:67], s[10:11], exec
	s_cselect_b32 s66, s90, s8
	s_add_i32 s66, s66, s89
	s_lshl_b32 s66, s66, 2
	s_or_b32 s66, s66, s88
	s_ashr_i32 s67, s66, 31
	s_lshl_b64 s[66:67], s[66:67], 15
	s_add_u32 s66, s29, s66
	s_addc_u32 s67, s30, s67
	s_lshl_b32 s65, s31, 4
	s_add_u32 s66, s66, s65
	s_addc_u32 s67, s67, 0
	s_add_i32 s95, s90, -1
	s_and_b32 s95, s95, 1
	s_xor_b32 s95, s95, 1
	s_mul_i32 s95, s95, 0x12400
	s_add_i32 s95, s95, s65
	s_add_i32 m0, s95, 0xa000
	s_nop 0
	global_load_lds_dwordx4 v134, s[66:67] nt
	global_load_lds_dwordx4 v134, s[66:67] offset:1024 nt
	global_load_lds_dwordx4 v134, s[66:67] offset:2048 nt
	global_load_lds_dwordx4 v134, s[66:67] offset:3072 nt
.Lvt_p_0:
	s_branch .LBB0_410
; #define LAS __attribute__((address_space(3)))
; #define RD_QD(dst, s0) _Pragma("unroll") for (int s_ = 0; s_ < 4; ++s_) { dst[s_] = *(const LAS bf16x8*)(B + CH_QD + i0 * 256 + (((2 * ((s0) + s_) + hi) ^ (i0 & 15)) << 4)); \
;                 dst[4 + s_] = *(const LAS bf16x8*)(B + CH_QD + i1 * 256 + (((2 * ((s0) + s_) + hi) ^ (i1 & 15)) << 4)); }
; #define DECAY(db_) do { f32x4 dc_[4]; _Pragma("unroll") for (int a4_ = 0; a4_ < 4; ++a4_) dc_[a4_] = *(const LAS f32x4*)(B + CH_DEC + ((db_) * 32 + 8 * a4_ + 4 * hi) * 4); \
;                 _Pragma("unroll") for (int a4_ = 0; a4_ < 4; ++a4_) _Pragma("unroll") for (int b4_ = 0; b4_ < 4; ++b4_) T[db_][a4_ * 4 + b4_] *= dc_[a4_][b4_]; } while (0)
; DI void phase_gla_chain(const Params& P, int l, int task0, int ntask_stride, LAS unsigned char* lds) {
;     ...
;             const int i0 = r32, i1 = 32 + r32; const int vv = wid * 32 + r32;
;             bf16x8 fa[8], fb[8], vf[4];
;             f32x16 o[2]; for (int x = 0; x < 16; ++x) { o[0][x] = 0.f; o[1][x] = 0.f; }
;     ...
;             RD_QD(fa, 0);
; #pragma unroll
;             for (int ks = 0; ks < 4; ++ks) vf[ks] = *(const LAS bf16x8*)(B + CH_VT + vv * 128 + (((2 * ks + hi) ^ ((vv >> 1) & 7)) << 4));
;             __builtin_amdgcn_sched_barrier(0);
;             RD_QD(fb, 4);
;             __builtin_amdgcn_sched_barrier(0);
;             MM_QD(fa, 0);
;             DECAY(0); DECAY(1);
;             __builtin_amdgcn_sched_barrier(0);
; #pragma unroll
;             for (int ks = 0; ks < 4; ++ks) { fa[ks] = *(const LAS bf16x8*)(B + CH_AM + i0 * 128 + (((2 * ks + hi) ^ ((i0 >> 1) & 7)) << 4)); fa[4 + ks] = *(const LAS bf16x8*)(B + CH_AM + i1 * 128 + (((2 * ks + hi) ^ ((i1 >> 1) & 7)) << 4)); }
;             __builtin_amdgcn_sched_barrier(0);
;             MM_QD(fb, 4);
;             DECAY(2); DECAY(3);
;             __builtin_amdgcn_sched_barrier(0);
.LBB0_409:
	s_mul_i32 s92, s92, 0x12400
	s_add_i32 s22, s92, 0
	v_add_u32_e32 v74, s22, v205
	v_add_u32_e32 v75, s22, v141
	v_add_u32_e32 v66, v74, v149
	v_add_u32_e32 v70, v75, v149
	v_add_u32_e32 v76, v74, v151
	ds_read_b128 v[66:69], v66
	ds_read_b128 v[70:73], v70
	v_add_u32_e32 v77, v75, v151
	ds_read_b128 v[182:185], v76
	ds_read_b128 v[186:189], v77
	v_add_u32_e32 v76, v74, v153
	v_add_u32_e32 v77, v75, v153
	ds_read_b128 v[190:193], v76
	ds_read_b128 v[194:197], v77
	v_add_u32_e32 v76, v74, v160
	v_add_u32_e32 v77, v75, v160
	ds_read_b128 v[198:201], v76
	ds_read_b128 v[208:211], v77
	v_add_u32_e32 v76, s22, v173
	v_add_u32_e32 v77, v76, v162
	v_add_u32_e32 v78, v76, v164
	ds_read_b128 v[110:113], v77 offset:40960
	ds_read_b128 v[106:109], v78 offset:40960
	v_add_u32_e32 v77, v76, v165
	v_add_u32_e32 v76, v76, v166
	ds_read_b128 v[102:105], v77 offset:40960
	ds_read_b128 v[98:101], v76 offset:40960
	v_add_u32_e32 v76, v74, v167
	v_add_u32_e32 v77, v75, v167
	ds_read_b128 v[212:215], v76
	ds_read_b128 v[216:219], v77
	v_add_u32_e32 v76, v74, v168
	v_add_u32_e32 v77, v75, v168
	ds_read_b128 v[220:223], v76
	ds_read_b128 v[130:133], v77
	v_add_u32_e32 v76, v74, v169
	v_add_u32_e32 v74, v74, v170
	v_add_u32_e32 v77, v75, v169
	ds_read_b128 v[126:129], v76
	ds_read_b128 v[122:125], v77
	v_add_u32_e32 v75, v75, v170
	ds_read_b128 v[118:121], v74
	ds_read_b128 v[114:117], v75
	v_cvt_pk_bf16_f32 v74, v2, v3
	v_cvt_pk_bf16_f32 v75, v4, v5
	v_cvt_pk_bf16_f32 v76, v6, v7
	v_cvt_pk_bf16_f32 v77, v8, v9
	v_cvt_pk_bf16_f32 v224, v10, v11
	v_cvt_pk_bf16_f32 v225, v12, v13
	s_waitcnt lgkmcnt(0)
	v_mfma_f32_32x32x16_bf16 v[82:97], v[66:69], v[74:77], 0
	v_cvt_pk_bf16_f32 v226, v14, v15
	v_cvt_pk_bf16_f32 v227, v16, v17
	v_add_u32_e32 v207, s22, v146
	v_add_u32_e32 v231, 0x12000, v207
	v_cvt_pk_bf16_f32 v228, v26, v27
	v_cvt_pk_bf16_f32 v229, v28, v29
	v_cvt_pk_bf16_f32 v230, v30, v31
	v_mfma_f32_32x32x16_bf16 v[66:81], v[70:73], v[74:77], 0
	v_mfma_f32_32x32x16_bf16 v[82:97], v[182:185], v[224:227], v[82:97]
	v_cvt_pk_bf16_f32 v182, v18, v19
	v_cvt_pk_bf16_f32 v183, v20, v21
	v_cvt_pk_bf16_f32 v184, v22, v23
	v_cvt_pk_bf16_f32 v185, v24, v25
	v_mfma_f32_32x32x16_bf16 v[66:81], v[186:189], v[224:227], v[66:81]
	ds_read_b128 v[186:189], v231 offset:64
	ds_read_b128 v[224:227], v231 offset:96
	ds_read_b128 v[232:235], v231
	ds_read_b128 v[236:239], v231 offset:32
	v_cvt_pk_bf16_f32 v231, v32, v33
	s_waitcnt lgkmcnt(0)
	v_pk_mul_f32 v[10:11], v[10:11], v[186:187]
	v_pk_mul_f32 v[12:13], v[12:13], v[188:189]
	v_pk_mul_f32 v[14:15], v[14:15], v[224:225]
	v_pk_mul_f32 v[6:7], v[6:7], v[236:237]
	v_pk_mul_f32 v[16:17], v[16:17], v[226:227]
	v_mfma_f32_32x32x16_bf16 v[82:97], v[190:193], v[182:185], v[82:97]
	v_mul_f32_e64 v8, v8, v238
	v_mul_f32_e64 v9, v9, v239
	v_mul_f32_e64 v4, v4, v234
	v_mul_f32_e64 v5, v5, v235
	v_mul_f32_e64 v2, v2, v232
	v_mul_f32_e64 v3, v3, v233
	v_mfma_f32_32x32x16_bf16 v[66:81], v[194:197], v[182:185], v[66:81]
	v_add_u32_e32 v194, 0x12080, v207
	ds_read_b128 v[182:185], v194 offset:64
	ds_read_b128 v[186:189], v194 offset:96
	ds_read_b128 v[190:193], v194
	ds_read_b128 v[194:197], v194 offset:32
	s_waitcnt lgkmcnt(0)
	v_pk_mul_f32 v[26:27], v[26:27], v[182:183]
	v_pk_mul_f32 v[30:31], v[30:31], v[186:187]
	v_pk_mul_f32 v[32:33], v[32:33], v[188:189]
	v_pk_mul_f32 v[22:23], v[22:23], v[194:195]
	v_pk_mul_f32 v[28:29], v[28:29], v[184:185]
	v_pk_mul_f32 v[24:25], v[24:25], v[196:197]
	v_pk_mul_f32 v[20:21], v[20:21], v[192:193]
	v_pk_mul_f32 v[18:19], v[18:19], v[190:191]
	v_mfma_f32_32x32x16_bf16 v[82:97], v[198:201], v[228:231], v[82:97]
	v_mfma_f32_32x32x16_bf16 v[66:81], v[208:211], v[228:231], v[66:81]
	v_add_u32_e32 v224, s22, v143
	v_add_u32_e32 v225, s22, v145
	v_add_u32_e32 v240, v224, v162
	v_add_u32_e32 v186, v225, v162
	v_add_u32_e32 v241, v224, v164
	v_add_u32_e32 v194, v225, v164
	v_add_u32_e32 v242, v224, v165
	v_add_u32_e32 v208, v225, v165
	v_add_u32_e32 v243, v224, v166
	v_add_u32_e32 v228, v225, v166
	ds_read_b128 v[182:185], v240 offset:16384
	ds_read_b128 v[186:189], v186 offset:16384
	ds_read_b128 v[190:193], v241 offset:16384
	ds_read_b128 v[194:197], v194 offset:16384
	ds_read_b128 v[198:201], v242 offset:16384
	ds_read_b128 v[208:211], v208 offset:16384
	ds_read_b128 v[224:227], v243 offset:16384
	ds_read_b128 v[228:231], v228 offset:16384
	v_cvt_pk_bf16_f32 v232, v34, v35
	v_cvt_pk_bf16_f32 v233, v36, v37
	v_cvt_pk_bf16_f32 v234, v38, v39
	v_cvt_pk_bf16_f32 v235, v40, v41
	s_nop 1
	v_mfma_f32_32x32x16_bf16 v[82:97], v[212:215], v[232:235], v[82:97]
	v_cvt_pk_bf16_f32 v212, v42, v43
	v_cvt_pk_bf16_f32 v213, v44, v45
	v_cvt_pk_bf16_f32 v214, v46, v47
	v_cvt_pk_bf16_f32 v215, v48, v49
	v_mfma_f32_32x32x16_bf16 v[66:81], v[216:219], v[232:235], v[66:81]
	v_cvt_pk_bf16_f32 v216, v50, v51
	v_cvt_pk_bf16_f32 v217, v52, v53
	v_cvt_pk_bf16_f32 v218, v54, v55
	v_cvt_pk_bf16_f32 v219, v56, v57
	v_mfma_f32_32x32x16_bf16 v[82:97], v[220:223], v[212:215], v[82:97]
	v_add_u32_e32 v223, 0x12100, v207
	v_add_u32_e32 v207, 0x12180, v207
	v_cvt_pk_bf16_f32 v220, v58, v59
	v_cvt_pk_bf16_f32 v221, v60, v61
	v_cvt_pk_bf16_f32 v222, v62, v63
	v_mfma_f32_32x32x16_bf16 v[66:81], v[130:133], v[212:215], v[66:81]
	ds_read_b128 v[130:133], v223 offset:64
	ds_read_b128 v[212:215], v223 offset:96
	ds_read_b128 v[232:235], v223
	ds_read_b128 v[236:239], v223 offset:32
	v_cvt_pk_bf16_f32 v223, v64, v65
	s_waitcnt lgkmcnt(0)
; #define LAS __attribute__((address_space(3)))
; DI int crow(int r, int hi) { return (r & 3) + 8 * (r >> 2) + 4 * hi; }
; DI unsigned pkbf(float a, float b) { f32x2 v = {a, b}; bfx2 r = __builtin_convertvector(v, bfx2); return __builtin_bit_cast(unsigned, r); }
; #define MM_KT(src, db0) _Pragma("unroll") for (int q_ = 0; q_ < 2; ++q_) { \
;                 _Pragma("unroll") for (int ks_ = 0; ks_ < 4; ++ks_) T[(db0) + q_] = __builtin_amdgcn_mfma_f32_32x32x16_bf16(src[q_ * 4 + ks_], vf[ks_], T[(db0) + q_], 0, 0, 0); }
; DI void phase_gla_chain(const Params& P, int l, int task0, int ntask_stride, LAS unsigned char* lds) {
;     ...
;             for (int ks = 0; ks < 4; ++ks) { fa[ks] = *(const LAS bf16x8*)(B + CH_AM + i0 * 128 + (((2 * ks + hi) ^ ((i0 >> 1) & 7)) << 4)); fa[4 + ks] = *(const LAS bf16x8*)(B + CH_AM + i1 * 128 + (((2 * ks + hi) ^ ((i1 >> 1) & 7)) << 4)); }
;             __builtin_amdgcn_sched_barrier(0);
;             MM_QD(fb, 4);
;             DECAY(2); DECAY(3);
;             __builtin_amdgcn_sched_barrier(0);
;             RD_KT(fb, 0);
;             __builtin_amdgcn_sched_barrier(0);
; #pragma unroll
;             for (int ks = 0; ks < 4; ++ks) { o[0] = __builtin_amdgcn_mfma_f32_32x32x16_bf16(fa[ks], vf[ks], o[0], 0, 0, 0); o[1] = __builtin_amdgcn_mfma_f32_32x32x16_bf16(fa[4 + ks], vf[ks], o[1], 0, 0, 0); }
;             __builtin_amdgcn_sched_barrier(0);
;             RD_KT(fa, 2);
;             __builtin_amdgcn_sched_barrier(0);
;             MM_KT(fb, 0);
;             __builtin_amdgcn_sched_barrier(0);
;             MM_KT(fa, 2);
;     ...
;             { const int cs = dir ? 63 - n : n; const size_t tokb = (size_t)sq * SEQL + cs * 64; const int odd = lane & 1;
;               bf16_t* ob = OFB + (size_t)dir * MTOK * 1024 + h * 256 + wid * 32 + (r32 & ~1);
; #pragma unroll
;               for (int ib = 0; ib < 2; ++ib)
; #pragma unroll
;                   for (int x = 0; x < 16; x += 2) { float ea_ = o[ib][x], eb_ = o[ib][x + 1]; asm volatile("" : "+v"(ea_), "+v"(eb_)); const float mine = odd ? eb_ : ea_, give = odd ? ea_ : eb_;
;                       const float got = __int_as_float(__builtin_amdgcn_update_dpp(0, __float_as_int(give), 0xB1, 0xF, 0xF, true));
;                       const unsigned w = odd ? pkbf(got, mine) : pkbf(mine, got);
;                       *(unsigned*)(ob + (tokb + ib * 32 + crow(x + odd, hi)) * 1024) = w; } }
	v_pk_mul_f32 v[42:43], v[42:43], v[130:131]
	v_pk_mul_f32 v[46:47], v[46:47], v[212:213]
	v_pk_mul_f32 v[48:49], v[48:49], v[214:215]
	v_pk_mul_f32 v[44:45], v[44:45], v[132:133]
	v_pk_mul_f32 v[38:39], v[38:39], v[236:237]
	v_mfma_f32_32x32x16_bf16 v[82:97], v[126:129], v[216:219], v[82:97]
	v_mul_f32_e64 v40, v40, v238
	v_mul_f32_e64 v41, v41, v239
	v_mul_f32_e64 v36, v36, v234
	v_mul_f32_e64 v37, v37, v235
	v_mul_f32_e64 v34, v34, v232
	v_mul_f32_e64 v35, v35, v233
	v_mfma_f32_32x32x16_bf16 v[66:81], v[122:125], v[216:219], v[66:81]
	ds_read_b128 v[122:125], v207 offset:64
	ds_read_b128 v[126:129], v207 offset:96
	ds_read_b128 v[130:133], v207
	ds_read_b128 v[212:215], v207 offset:32
	s_waitcnt lgkmcnt(0)
	v_pk_mul_f32 v[58:59], v[58:59], v[122:123]
	v_pk_mul_f32 v[62:63], v[62:63], v[126:127]
	v_pk_mul_f32 v[64:65], v[64:65], v[128:129]
	v_pk_mul_f32 v[54:55], v[54:55], v[212:213]
	v_pk_mul_f32 v[60:61], v[60:61], v[124:125]
	v_pk_mul_f32 v[56:57], v[56:57], v[214:215]
	v_pk_mul_f32 v[52:53], v[52:53], v[132:133]
	v_pk_mul_f32 v[50:51], v[50:51], v[130:131]
	v_mfma_f32_32x32x16_bf16 v[82:97], v[118:121], v[220:223], v[82:97]
	v_mfma_f32_32x32x16_bf16 v[66:81], v[114:117], v[220:223], v[66:81]
	ds_read_b128 v[114:117], v240 offset:24576
	ds_read_b128 v[118:121], v240 offset:28672
	ds_read_b128 v[122:125], v241 offset:24576
	ds_read_b128 v[126:129], v241 offset:28672
	ds_read_b128 v[130:133], v242 offset:24576
	ds_read_b128 v[212:215], v242 offset:28672
	ds_read_b128 v[216:219], v243 offset:24576
	ds_read_b128 v[220:223], v243 offset:28672
	v_mfma_f32_32x32x16_bf16 v[82:97], v[182:185], v[110:113], v[82:97]
	v_mfma_f32_32x32x16_bf16 v[66:81], v[186:189], v[110:113], v[66:81]
	v_mfma_f32_32x32x16_bf16 v[82:97], v[190:193], v[106:109], v[82:97]
	v_mfma_f32_32x32x16_bf16 v[66:81], v[194:197], v[106:109], v[66:81]
	v_mfma_f32_32x32x16_bf16 v[82:97], v[198:201], v[102:105], v[82:97]
	v_mfma_f32_32x32x16_bf16 v[66:81], v[208:211], v[102:105], v[66:81]
	v_mfma_f32_32x32x16_bf16 v[82:97], v[224:227], v[98:101], v[82:97]
	v_mfma_f32_32x32x16_bf16 v[66:81], v[228:231], v[98:101], v[66:81]
	ds_read_b128 v[182:185], v240 offset:32768
	ds_read_b128 v[186:189], v240 offset:36864
	ds_read_b128 v[190:193], v241 offset:32768
	ds_read_b128 v[194:197], v241 offset:36864
	ds_read_b128 v[198:201], v242 offset:32768
	ds_read_b128 v[208:211], v242 offset:36864
	ds_read_b128 v[224:227], v243 offset:32768
	ds_read_b128 v[228:231], v243 offset:36864
	s_waitcnt lgkmcnt(0)
	v_mfma_f32_32x32x16_bf16 v[2:17], v[114:117], v[110:113], v[2:17]
	v_mfma_f32_32x32x16_bf16 v[18:33], v[118:121], v[110:113], v[18:33]
	v_mfma_f32_32x32x16_bf16 v[2:17], v[122:125], v[106:109], v[2:17]
	v_mfma_f32_32x32x16_bf16 v[18:33], v[126:129], v[106:109], v[18:33]
	v_mfma_f32_32x32x16_bf16 v[2:17], v[130:133], v[102:105], v[2:17]
	v_mfma_f32_32x32x16_bf16 v[18:33], v[212:215], v[102:105], v[18:33]
	v_mfma_f32_32x32x16_bf16 v[2:17], v[216:219], v[98:101], v[2:17]
	v_mfma_f32_32x32x16_bf16 v[18:33], v[220:223], v[98:101], v[18:33]
	s_add_i32 s64, s8, 1
	s_and_b64 s[22:23], s[10:11], exec
	s_cselect_b32 s22, s91, s64
	s_lshl_b32 s22, s22, 6
	s_add_u32 s23, s20, s22
	v_cndmask_b32_e64 v114, v82, v83, s[0:1]
	s_addc_u32 s22, s21, 0
	v_mfma_f32_32x32x16_bf16 v[34:49], v[182:185], v[110:113], v[34:49]
	v_mov_b32_dpp v114, v114 quad_perm:[1,0,3,2] row_mask:0xf bank_mask:0xf bound_ctrl:1
	v_cndmask_b32_e64 v83, v83, v114, s[0:1]
	v_cndmask_b32_e64 v82, v114, v82, s[0:1]
	v_cvt_pk_bf16_f32 v114, v82, v83
	v_readfirstlane_b32 s98, v158
	v_readfirstlane_b32 s99, v159
	v_and_b32_e32 v244, 30, v137
	v_lshlrev_b32_e32 v244, 1, v244
	v_lshl_add_u32 v244, v136, 11, v244
	s_lshl_b32 s100, s23, 11
	s_add_u32 s98, s98, s100
	s_addc_u32 s99, s99, 0
	s_add_u32 s100, s98, 0x800
	s_addc_u32 s101, s99, 0
	global_store_dword v244, v114, s[100:101] offset:-2048
	v_mov_b32_e32 v82, v84
	v_mfma_f32_32x32x16_bf16 v[50:65], v[186:189], v[110:113], v[50:65]
	v_cndmask_b32_e64 v83, v82, v85, s[0:1]
	s_add_i32 s8, s8, -1
	s_add_i32 s90, s90, 1
	v_mov_b32_dpp v83, v83 quad_perm:[1,0,3,2] row_mask:0xf bank_mask:0xf bound_ctrl:1
	v_cndmask_b32_e64 v84, v85, v83, s[0:1]
	v_cndmask_b32_e64 v82, v83, v82, s[0:1]
	v_cvt_pk_bf16_f32 v84, v82, v84
	global_store_dword v244, v84, s[100:101] offset:2048
	v_mov_b32_e32 v82, v87
	v_mfma_f32_32x32x16_bf16 v[34:49], v[190:193], v[106:109], v[34:49]
	v_cndmask_b32_e64 v83, v86, v82, s[0:1]
	s_nop 1
	v_mov_b32_dpp v83, v83 quad_perm:[1,0,3,2] row_mask:0xf bank_mask:0xf bound_ctrl:1
	v_cndmask_b32_e64 v82, v82, v83, s[0:1]
	v_cndmask_b32_e64 v83, v83, v86, s[0:1]
	v_cvt_pk_bf16_f32 v84, v83, v82
	s_add_u32 s100, s98, 0x4800
	s_addc_u32 s101, s99, 0
	global_store_dword v244, v84, s[100:101] offset:-2048
	v_mov_b32_e32 v82, v88
	v_mfma_f32_32x32x16_bf16 v[50:65], v[194:197], v[106:109], v[50:65]
	v_cndmask_b32_e64 v83, v82, v89, s[0:1]
	s_nop 1
	v_mov_b32_dpp v83, v83 quad_perm:[1,0,3,2] row_mask:0xf bank_mask:0xf bound_ctrl:1
	v_cndmask_b32_e64 v84, v89, v83, s[0:1]
	v_cndmask_b32_e64 v82, v83, v82, s[0:1]
	v_cvt_pk_bf16_f32 v84, v82, v84
	global_store_dword v244, v84, s[100:101] offset:2048
	v_mov_b32_e32 v82, v90
	v_mfma_f32_32x32x16_bf16 v[34:49], v[198:201], v[102:105], v[34:49]
	v_cndmask_b32_e64 v83, v82, v91, s[0:1]
	s_nop 1
	v_mov_b32_dpp v83, v83 quad_perm:[1,0,3,2] row_mask:0xf bank_mask:0xf bound_ctrl:1
	v_cndmask_b32_e64 v84, v91, v83, s[0:1]
	v_cndmask_b32_e64 v82, v83, v82, s[0:1]
	v_cvt_pk_bf16_f32 v84, v82, v84
	s_add_u32 s100, s98, 0x8800
	s_addc_u32 s101, s99, 0
	global_store_dword v244, v84, s[100:101] offset:-2048
	v_mov_b32_e32 v82, v93
; DI int crow(int r, int hi) { return (r & 3) + 8 * (r >> 2) + 4 * hi; }
; DI unsigned pkbf(float a, float b) { f32x2 v = {a, b}; bfx2 r = __builtin_convertvector(v, bfx2); return __builtin_bit_cast(unsigned, r); }
; DI void phase_gla_chain(const Params& P, int l, int task0, int ntask_stride, LAS unsigned char* lds) {
;     ...
;         __syncthreads();
;         CH_ISSUE(0, 0);
;         for (int n = 0; n < 64; ++n) {
;             const int b = n & 1;
;             if (n == 0) asm volatile("s_waitcnt vmcnt(0)" ::: "memory"); else asm volatile("s_waitcnt vmcnt(16)" ::: "memory");
;             __builtin_amdgcn_s_barrier();
;             asm volatile("" ::: "memory");
;             if (n + 1 < 64) CH_ISSUE(n + 1, b ^ 1);
;     ...
;             { const int cs = dir ? 63 - n : n; const size_t tokb = (size_t)sq * SEQL + cs * 64; const int odd = lane & 1;
;               bf16_t* ob = OFB + (size_t)dir * MTOK * 1024 + h * 256 + wid * 32 + (r32 & ~1);
; #pragma unroll
;               for (int ib = 0; ib < 2; ++ib)
; #pragma unroll
;                   for (int x = 0; x < 16; x += 2) { float ea_ = o[ib][x], eb_ = o[ib][x + 1]; asm volatile("" : "+v"(ea_), "+v"(eb_)); const float mine = odd ? eb_ : ea_, give = odd ? ea_ : eb_;
;                       const float got = __int_as_float(__builtin_amdgcn_update_dpp(0, __float_as_int(give), 0xB1, 0xF, 0xF, true));
;                       const unsigned w = odd ? pkbf(got, mine) : pkbf(mine, got);
;                       *(unsigned*)(ob + (tokb + ib * 32 + crow(x + odd, hi)) * 1024) = w; } }
	v_mfma_f32_32x32x16_bf16 v[50:65], v[208:211], v[102:105], v[50:65]
	v_cndmask_b32_e64 v83, v92, v82, s[0:1]
	s_nop 1
	v_mov_b32_dpp v83, v83 quad_perm:[1,0,3,2] row_mask:0xf bank_mask:0xf bound_ctrl:1
	v_cndmask_b32_e64 v82, v82, v83, s[0:1]
	v_cndmask_b32_e64 v83, v83, v92, s[0:1]
	v_cvt_pk_bf16_f32 v84, v83, v82
	global_store_dword v244, v84, s[100:101] offset:2048
	v_mov_b32_e32 v82, v94
	v_mfma_f32_32x32x16_bf16 v[34:49], v[224:227], v[98:101], v[34:49]
	v_cndmask_b32_e64 v83, v82, v95, s[0:1]
	s_nop 1
	v_mov_b32_dpp v83, v83 quad_perm:[1,0,3,2] row_mask:0xf bank_mask:0xf bound_ctrl:1
	v_cndmask_b32_e64 v84, v95, v83, s[0:1]
	v_cndmask_b32_e64 v82, v83, v82, s[0:1]
	v_cvt_pk_bf16_f32 v84, v82, v84
	s_add_u32 s100, s98, 0xc800
	s_addc_u32 s101, s99, 0
	global_store_dword v244, v84, s[100:101] offset:-2048
	v_mov_b32_e32 v82, v96
	v_mfma_f32_32x32x16_bf16 v[50:65], v[228:231], v[98:101], v[50:65]
	v_cndmask_b32_e64 v83, v82, v97, s[0:1]
	s_nop 1
	v_mov_b32_dpp v83, v83 quad_perm:[1,0,3,2] row_mask:0xf bank_mask:0xf bound_ctrl:1
	v_cndmask_b32_e64 v84, v97, v83, s[0:1]
	v_cndmask_b32_e64 v82, v83, v82, s[0:1]
	v_cvt_pk_bf16_f32 v84, v82, v84
	global_store_dword v244, v84, s[100:101] offset:2048
	s_or_b32 s23, s23, 32
	v_cndmask_b32_e64 v82, v66, v67, s[0:1]
	s_nop 0
	v_mov_b32_dpp v82, v82 quad_perm:[1,0,3,2] row_mask:0xf bank_mask:0xf bound_ctrl:1
	v_cndmask_b32_e64 v67, v67, v82, s[0:1]
	v_cndmask_b32_e64 v66, v82, v66, s[0:1]
	v_cvt_pk_bf16_f32 v82, v66, v67
	s_add_u32 s100, s98, 0x10800
	s_addc_u32 s101, s99, 0
	global_store_dword v244, v82, s[100:101] offset:-2048
	v_mov_b32_e32 v66, v68
	s_nop 0
	v_cndmask_b32_e64 v67, v66, v69, s[0:1]
	s_nop 1
	v_mov_b32_dpp v67, v67 quad_perm:[1,0,3,2] row_mask:0xf bank_mask:0xf bound_ctrl:1
	v_cndmask_b32_e64 v68, v69, v67, s[0:1]
	v_cndmask_b32_e64 v66, v67, v66, s[0:1]
	v_cvt_pk_bf16_f32 v68, v66, v68
	global_store_dword v244, v68, s[100:101] offset:2048
	v_mov_b32_e32 v66, v70
	s_nop 0
	v_cndmask_b32_e64 v67, v66, v71, s[0:1]
	s_nop 1
	v_mov_b32_dpp v67, v67 quad_perm:[1,0,3,2] row_mask:0xf bank_mask:0xf bound_ctrl:1
	v_cndmask_b32_e64 v68, v71, v67, s[0:1]
	v_cndmask_b32_e64 v66, v67, v66, s[0:1]
	v_cvt_pk_bf16_f32 v68, v66, v68
	s_add_u32 s100, s98, 0x14800
	s_addc_u32 s101, s99, 0
	global_store_dword v244, v68, s[100:101] offset:-2048
	v_mov_b32_e32 v66, v73
	s_nop 0
	v_cndmask_b32_e64 v67, v72, v66, s[0:1]
	s_nop 1
	v_mov_b32_dpp v67, v67 quad_perm:[1,0,3,2] row_mask:0xf bank_mask:0xf bound_ctrl:1
	v_cndmask_b32_e64 v66, v66, v67, s[0:1]
	v_cndmask_b32_e64 v67, v67, v72, s[0:1]
	v_cvt_pk_bf16_f32 v68, v67, v66
	global_store_dword v244, v68, s[100:101] offset:2048
	v_mov_b32_e32 v66, v74
	s_nop 0
	v_cndmask_b32_e64 v67, v66, v75, s[0:1]
	s_nop 1
	v_mov_b32_dpp v67, v67 quad_perm:[1,0,3,2] row_mask:0xf bank_mask:0xf bound_ctrl:1
	v_cndmask_b32_e64 v68, v75, v67, s[0:1]
	v_cndmask_b32_e64 v66, v67, v66, s[0:1]
	v_cvt_pk_bf16_f32 v68, v66, v68
	s_add_u32 s100, s98, 0x18800
	s_addc_u32 s101, s99, 0
	global_store_dword v244, v68, s[100:101] offset:-2048
	v_mov_b32_e32 v66, v76
	s_nop 0
	v_cndmask_b32_e64 v67, v66, v77, s[0:1]
	s_nop 1
	v_mov_b32_dpp v67, v67 quad_perm:[1,0,3,2] row_mask:0xf bank_mask:0xf bound_ctrl:1
	v_cndmask_b32_e64 v68, v77, v67, s[0:1]
	v_cndmask_b32_e64 v66, v67, v66, s[0:1]
	v_cvt_pk_bf16_f32 v68, v66, v68
	global_store_dword v244, v68, s[100:101] offset:2048
	v_mov_b32_e32 v66, v79
	s_nop 0
	v_cndmask_b32_e64 v67, v78, v66, s[0:1]
	s_nop 1
	v_mov_b32_dpp v67, v67 quad_perm:[1,0,3,2] row_mask:0xf bank_mask:0xf bound_ctrl:1
	v_cndmask_b32_e64 v66, v66, v67, s[0:1]
	v_cndmask_b32_e64 v67, v67, v78, s[0:1]
	v_cvt_pk_bf16_f32 v68, v67, v66
	s_add_u32 s100, s98, 0x1c800
	s_addc_u32 s101, s99, 0
	global_store_dword v244, v68, s[100:101] offset:-2048
	v_mov_b32_e32 v66, v81
	s_nop 0
	v_cndmask_b32_e64 v67, v80, v66, s[0:1]
	s_nop 1
	v_mov_b32_dpp v67, v67 quad_perm:[1,0,3,2] row_mask:0xf bank_mask:0xf bound_ctrl:1
	v_cndmask_b32_e64 v66, v66, v67, s[0:1]
	v_cndmask_b32_e64 v67, v67, v80, s[0:1]
	v_cvt_pk_bf16_f32 v68, v67, v66
	global_store_dword v244, v68, s[100:101] offset:2048
	s_cmp_lt_i32 s8, 0
	s_cbranch_scc1 .Lvt_b_0
	s_and_b64 s[66:67], s[10:11], exec
	s_cselect_b32 s66, s90, s8
	s_add_i32 s66, s66, s89
	s_lshl_b32 s66, s66, 2
	s_or_b32 s66, s66, s88
	s_ashr_i32 s67, s66, 31
	s_lshl_b64 s[66:67], s[66:67], 15
	s_add_u32 s66, s29, s66
	s_addc_u32 s67, s30, s67
	s_lshl_b32 s65, s31, 4
	s_add_u32 s66, s66, s65
	s_addc_u32 s67, s67, 0
	s_add_i32 s95, s90, -1
	s_and_b32 s95, s95, 1
	s_xor_b32 s95, s95, 1
	s_mul_i32 s95, s95, 0x12400
	s_add_i32 s95, s95, s65
	s_add_i32 m0, s95, 0xa000
	s_nop 0
	global_load_lds_dwordx4 v134, s[66:67] nt
	global_load_lds_dwordx4 v134, s[66:67] offset:1024 nt
	global_load_lds_dwordx4 v134, s[66:67] offset:2048 nt
	global_load_lds_dwordx4 v134, s[66:67] offset:3072 nt
.Lvt_b_0:
	s_cmp_eq_u32 s8, -2
	s_cbranch_scc1 .LBB0_403
.LBB0_410:
	s_add_i32 s91, s90, -1
	s_cmp_eq_u32 s8, -1
	s_cbranch_scc1 .Lvt_w16_0
	s_waitcnt vmcnt(20)
	s_branch .Lvt_wd_0
.Lvt_w16_0:
	s_waitcnt vmcnt(16)
.Lvt_wd_0:
	s_barrier
	s_and_b32 s92, s91, 1
	s_cmp_eq_u32 s8, -1
	s_cbranch_scc1 .LBB0_409
	s_and_b64 s[22:23], s[10:11], exec
	s_cselect_b32 s22, s90, s8
	s_add_i32 s22, s22, s89
	s_lshl_b32 s22, s22, 2
	s_or_b32 s96, s22, s88
	s_ashr_i32 s97, s96, 31
	s_add_u32 s22, s25, s96
	s_addc_u32 s23, 0, s97
	s_mul_i32 s93, s23, 0xa000
	s_mul_hi_u32 vcc_lo, s22, 0xa000
	s_add_i32 vcc_lo, vcc_lo, s93
	s_mul_i32 s93, s22, 0xa000
	s_add_u32 vcc_hi, s27, s93
	s_addc_u32 vcc_lo, s28, vcc_lo
	s_lshl_b64 s[96:97], s[96:97], 15
	s_add_u32 s68, s29, s96
	s_addc_u32 s69, s30, s97
	s_xor_b32 s93, s92, 1
	s_mul_i32 s93, s93, 0x12400
	s_add_i32 s93, s93, 0
	v_add_u32_e32 v245, 0x400, v134
	v_add_u32_e32 v246, 0x800, v134
	v_add_u32_e32 v247, 0xc00, v134
	v_add_u32_e32 v248, 0x1000, v134
	s_lshl_b32 s32, s31, 4
	s_lshl_b32 s98, s31, 2
	s_add_i32 s98, s98, s32
	s_add_u32 s100, vcc_hi, s98
	s_addc_u32 s101, vcc_lo, 0
	s_add_i32 s99, s93, s98
	s_add_i32 m0, s99, 0x0
	s_nop 0
	global_load_lds_dwordx4 v134, s[100:101] nt
	s_add_i32 m0, s99, 0x400
	s_nop 0
	global_load_lds_dwordx4 v245, s[100:101] nt
	s_add_i32 m0, s99, 0x800
	s_nop 0
	global_load_lds_dwordx4 v246, s[100:101] nt
	s_add_i32 m0, s99, 0xc00
	s_nop 0
	global_load_lds_dwordx4 v247, s[100:101] nt
	s_add_i32 m0, s99, 0x1000
	s_nop 0
	global_load_lds_dwordx4 v248, s[100:101] nt
	s_and_b64 vcc, exec, s[2:3]
	s_cbranch_vccnz .LBB0_409
	s_add_i32 s64, s93, s31
	s_lshl_b64 s[22:23], s[22:23], 9
	s_add_i32 m0, s64, 0x12000
	v_lshl_add_u64 v[66:67], v[156:157], 0, s[22:23]
	global_load_lds_dword v[66:67], off
	s_branch .LBB0_409

; #define LAS __attribute__((address_space(3)))
; #define RD_QD(dst, s0) _Pragma("unroll") for (int s_ = 0; s_ < 4; ++s_) { dst[s_] = *(const LAS bf16x8*)(B + CH_QD + i0 * 256 + (((2 * ((s0) + s_) + hi) ^ (i0 & 15)) << 4)); \
;                 dst[4 + s_] = *(const LAS bf16x8*)(B + CH_QD + i1 * 256 + (((2 * ((s0) + s_) + hi) ^ (i1 & 15)) << 4)); }
; #define DECAY(db_) do { f32x4 dc_[4]; _Pragma("unroll") for (int a4_ = 0; a4_ < 4; ++a4_) dc_[a4_] = *(const LAS f32x4*)(B + CH_DEC + ((db_) * 32 + 8 * a4_ + 4 * hi) * 4); \
;                 _Pragma("unroll") for (int a4_ = 0; a4_ < 4; ++a4_) _Pragma("unroll") for (int b4_ = 0; b4_ < 4; ++b4_) T[db_][a4_ * 4 + b4_] *= dc_[a4_][b4_]; } while (0)
; DI void phase_gla_chain(const Params& P, int l, int task0, int ntask_stride, LAS unsigned char* lds) {
;     ...
;         const int dir = task & 1, h = (task >> 1) & 3, sq = task >> 3;
;         f32x16 T[4]; for (int d = 0; d < 4; ++d) for (int x = 0; x < 16; ++x) T[d][x] = 0.f;
;     ...
;             const int i0 = r32, i1 = 32 + r32; const int vv = wid * 32 + r32;
;             bf16x8 fa[8], fb[8], vf[4];
;             f32x16 o[2]; for (int x = 0; x < 16; ++x) { o[0][x] = 0.f; o[1][x] = 0.f; }
;     ...
;             RD_QD(fa, 0);
; #pragma unroll
;             for (int ks = 0; ks < 4; ++ks) vf[ks] = *(const LAS bf16x8*)(B + CH_VT + vv * 128 + (((2 * ks + hi) ^ ((vv >> 1) & 7)) << 4));
;             __builtin_amdgcn_sched_barrier(0);
;             RD_QD(fb, 4);
;             __builtin_amdgcn_sched_barrier(0);
;             MM_QD(fa, 0);
;             DECAY(0); DECAY(1);
;             __builtin_amdgcn_sched_barrier(0);
; #pragma unroll
;             for (int ks = 0; ks < 4; ++ks) { fa[ks] = *(const LAS bf16x8*)(B + CH_AM + i0 * 128 + (((2 * ks + hi) ^ ((i0 >> 1) & 7)) << 4)); fa[4 + ks] = *(const LAS bf16x8*)(B + CH_AM + i1 * 128 + (((2 * ks + hi) ^ ((i1 >> 1) & 7)) << 4)); }
;             __builtin_amdgcn_sched_barrier(0);
;             MM_QD(fb, 4);
;             DECAY(2); DECAY(3);
;             __builtin_amdgcn_sched_barrier(0);
.LBB0_970:
	ds_read_b128 v[2:5], v176
	ds_read_b128 v[6:9], v177
	ds_read_b128 v[10:13], v178
	ds_read_b128 v[14:17], v179
	ds_read_b128 v[18:21], v180
	ds_read_b128 v[22:25], v181
	v_add_u32_e32 v26, v203, v160
	v_add_u32_e32 v30, v147, v160
	ds_read_b128 v[26:29], v26
	ds_read_b128 v[34:37], v30
	v_add_u32_e32 v30, v174, v162
	v_add_u32_e32 v31, v174, v164
	ds_read_b128 v[110:113], v30 offset:40960
	ds_read_b128 v[106:109], v31 offset:40960
	v_add_u32_e32 v30, v174, v165
	v_add_u32_e32 v31, v174, v166
	ds_read_b128 v[102:105], v30 offset:40960
	ds_read_b128 v[98:101], v31 offset:40960
	s_ashr_i32 s21, s20, 31
	s_lshl_b32 s8, s80, 9
	s_lshl_b64 s[20:21], s[20:21], 12
	v_lshl_add_u64 v[158:159], v[154:155], 0, s[8:9]
	v_add_u32_e32 v30, v203, v167
	v_add_u32_e32 v31, v147, v167
	ds_read_b128 v[38:41], v30
	ds_read_b128 v[42:45], v31
	v_add_u32_e32 v30, v203, v168
	v_add_u32_e32 v31, v147, v168
	ds_read_b128 v[46:49], v30
	ds_read_b128 v[50:53], v31
	v_add_u32_e32 v30, v203, v169
	v_add_u32_e32 v31, v147, v169
	ds_read_b128 v[54:57], v30
	ds_read_b128 v[58:61], v31
	v_add_u32_e32 v30, v203, v170
	v_add_u32_e32 v31, v147, v170
	ds_read_b128 v[62:65], v30
	ds_read_b128 v[114:117], v31
	v_mov_b64_e32 v[120:121], s[6:7]
	v_mov_b64_e32 v[118:119], s[4:5]
	v_add_u32_e32 v198, 0, v146
	s_waitcnt lgkmcnt(0)
	v_mfma_f32_32x32x16_bf16 v[82:97], v[2:5], v[118:121], 0
	v_mfma_f32_32x32x16_bf16 v[66:81], v[6:9], v[118:121], 0
	v_mfma_f32_32x32x16_bf16 v[82:97], v[10:13], v[118:121], v[82:97]
	v_add_u32_e32 v10, 0x12000, v198
	ds_read_b128 v[2:5], v10 offset:64
	ds_read_b128 v[6:9], v10 offset:96
	s_waitcnt lgkmcnt(0)
	v_mul_f32_e64 v12, v4, 0
	v_mul_f32_e64 v13, v5, 0
	v_mfma_f32_32x32x16_bf16 v[66:81], v[14:17], v[118:121], v[66:81]
	v_mul_f32_e64 v16, v8, 0
	v_mul_f32_e64 v17, v9, 0
	v_mul_f32_e64 v14, v6, 0
	v_mul_f32_e64 v15, v7, 0
	v_mfma_f32_32x32x16_bf16 v[82:97], v[18:21], v[118:121], v[82:97]
	ds_read_b128 v[18:21], v10 offset:32
	ds_read_b128 v[30:33], v10
	v_mul_f32_e64 v10, v2, 0
	v_mul_f32_e64 v11, v3, 0
	v_add_u32_e32 v2, 0x12080, v198
	s_waitcnt lgkmcnt(0)
	v_pk_mul_f32 v[8:9], v[20:21], 0 op_sel_hi:[1,0]
	v_pk_mul_f32 v[6:7], v[18:19], 0 op_sel_hi:[1,0]
	v_pk_mul_f32 v[4:5], v[32:33], 0 op_sel_hi:[1,0]
	v_mfma_f32_32x32x16_bf16 v[66:81], v[22:25], v[118:121], v[66:81]
	ds_read_b128 v[18:21], v2 offset:64
	ds_read_b128 v[22:25], v2 offset:96
	ds_read_b128 v[122:125], v2
	ds_read_b128 v[126:129], v2 offset:32
	v_mul_f32_e64 v2, v30, 0
	v_mul_f32_e64 v3, v31, 0
	s_waitcnt lgkmcnt(0)
	v_pk_mul_f32 v[32:33], v[24:25], 0 op_sel_hi:[1,0]
	v_pk_mul_f32 v[30:31], v[22:23], 0 op_sel_hi:[1,0]
	v_pk_mul_f32 v[24:25], v[128:129], 0 op_sel_hi:[1,0]
	v_pk_mul_f32 v[22:23], v[126:127], 0 op_sel_hi:[1,0]
	v_mfma_f32_32x32x16_bf16 v[82:97], v[26:29], v[118:121], v[82:97]
	v_mul_f32_e64 v28, v20, 0
	v_mul_f32_e64 v29, v21, 0
	v_mul_f32_e64 v20, v124, 0
	v_mul_f32_e64 v21, v125, 0
	v_mul_f32_e64 v26, v18, 0
	v_mul_f32_e64 v27, v19, 0
	v_pk_mul_f32 v[18:19], v[122:123], 0 op_sel_hi:[1,0]
	v_mfma_f32_32x32x16_bf16 v[66:81], v[34:37], v[118:121], v[66:81]
	v_add_u32_e32 v199, v171, v162
	v_add_u32_e32 v34, v172, v162
	ds_read_b128 v[122:125], v199 offset:16384
	ds_read_b128 v[126:129], v34 offset:16384
	v_add_u32_e32 v232, v171, v164
	v_add_u32_e32 v34, v172, v164
	ds_read_b128 v[130:133], v232 offset:16384
	ds_read_b128 v[182:185], v34 offset:16384
	v_add_u32_e32 v233, v171, v165
	v_add_u32_e32 v34, v172, v165
	v_add_u32_e32 v234, v171, v166
	ds_read_b128 v[186:189], v233 offset:16384
	ds_read_b128 v[190:193], v34 offset:16384
	v_add_u32_e32 v34, v172, v166
	ds_read_b128 v[194:197], v234 offset:16384
	ds_read_b128 v[204:207], v34 offset:16384
	v_mfma_f32_32x32x16_bf16 v[82:97], v[38:41], v[118:121], v[82:97]
	v_mfma_f32_32x32x16_bf16 v[66:81], v[42:45], v[118:121], v[66:81]
	v_add_u32_e32 v42, 0x12100, v198
	ds_read_b128 v[34:37], v42 offset:64
	ds_read_b128 v[38:41], v42 offset:96
	s_waitcnt lgkmcnt(0)
	v_mul_f32_e64 v44, v36, 0
	v_mul_f32_e64 v45, v37, 0
	v_mfma_f32_32x32x16_bf16 v[82:97], v[46:49], v[118:121], v[82:97]
	v_mul_f32_e64 v48, v40, 0
	v_mul_f32_e64 v49, v41, 0
	v_mul_f32_e64 v46, v38, 0
	v_mul_f32_e64 v47, v39, 0
	v_mfma_f32_32x32x16_bf16 v[66:81], v[50:53], v[118:121], v[66:81]
	v_mfma_f32_32x32x16_bf16 v[82:97], v[54:57], v[118:121], v[82:97]
	ds_read_b128 v[50:53], v42 offset:32
	ds_read_b128 v[54:57], v42
	v_mul_f32_e64 v42, v34, 0
	v_mul_f32_e64 v43, v35, 0
	v_add_u32_e32 v34, 0x12180, v198
	s_waitcnt lgkmcnt(0)
	v_pk_mul_f32 v[40:41], v[52:53], 0 op_sel_hi:[1,0]
	v_pk_mul_f32 v[38:39], v[50:51], 0 op_sel_hi:[1,0]
	v_pk_mul_f32 v[36:37], v[56:57], 0 op_sel_hi:[1,0]
	v_mfma_f32_32x32x16_bf16 v[66:81], v[58:61], v[118:121], v[66:81]
	ds_read_b128 v[50:53], v34 offset:64
	ds_read_b128 v[58:61], v34 offset:96
	ds_read_b128 v[208:211], v34
	ds_read_b128 v[212:215], v34 offset:32
	v_mul_f32_e64 v34, v54, 0
	v_mul_f32_e64 v35, v55, 0
	s_waitcnt lgkmcnt(0)
; DI int crow(int r, int hi) { return (r & 3) + 8 * (r >> 2) + 4 * hi; }
; DI unsigned pkbf(float a, float b) { f32x2 v = {a, b}; bfx2 r = __builtin_convertvector(v, bfx2); return __builtin_bit_cast(unsigned, r); }
; #define RD_KT(dst, db0) _Pragma("unroll") for (int q_ = 0; q_ < 2; ++q_) { const int d_ = ((db0) + q_) * 32 + r32; \
;                 _Pragma("unroll") for (int ks_ = 0; ks_ < 4; ++ks_) dst[q_ * 4 + ks_] = *(const LAS bf16x8*)(B + CH_KT + d_ * 128 + (((2 * ks_ + hi) ^ ((d_ >> 1) & 7)) << 4)); }
; #define MM_KT(src, db0) _Pragma("unroll") for (int q_ = 0; q_ < 2; ++q_) { \
;                 _Pragma("unroll") for (int ks_ = 0; ks_ < 4; ++ks_) T[(db0) + q_] = __builtin_amdgcn_mfma_f32_32x32x16_bf16(src[q_ * 4 + ks_], vf[ks_], T[(db0) + q_], 0, 0, 0); }
; DI void phase_gla_chain(const Params& P, int l, int task0, int ntask_stride, LAS unsigned char* lds) {
;     ...
;             RD_KT(fb, 0);
;             __builtin_amdgcn_sched_barrier(0);
; #pragma unroll
;             for (int ks = 0; ks < 4; ++ks) { o[0] = __builtin_amdgcn_mfma_f32_32x32x16_bf16(fa[ks], vf[ks], o[0], 0, 0, 0); o[1] = __builtin_amdgcn_mfma_f32_32x32x16_bf16(fa[4 + ks], vf[ks], o[1], 0, 0, 0); }
;             __builtin_amdgcn_sched_barrier(0);
;             RD_KT(fa, 2);
;             __builtin_amdgcn_sched_barrier(0);
;             MM_KT(fb, 0);
;             __builtin_amdgcn_sched_barrier(0);
;             MM_KT(fa, 2);
;     ...
;             { const int cs = dir ? 63 - n : n; const size_t tokb = (size_t)sq * SEQL + cs * 64; const int odd = lane & 1;
;               bf16_t* ob = OFB + (size_t)dir * MTOK * 1024 + h * 256 + wid * 32 + (r32 & ~1);
; #pragma unroll
;               for (int ib = 0; ib < 2; ++ib)
; #pragma unroll
;                   for (int x = 0; x < 16; x += 2) { float ea_ = o[ib][x], eb_ = o[ib][x + 1]; asm volatile("" : "+v"(ea_), "+v"(eb_)); const float mine = odd ? eb_ : ea_, give = odd ? ea_ : eb_;
;                       const float got = __int_as_float(__builtin_amdgcn_update_dpp(0, __float_as_int(give), 0xB1, 0xF, 0xF, true));
;                       const unsigned w = odd ? pkbf(got, mine) : pkbf(mine, got);
;                       *(unsigned*)(ob + (tokb + ib * 32 + crow(x + odd, hi)) * 1024) = w; } }
	v_pk_mul_f32 v[56:57], v[214:215], 0 op_sel_hi:[1,0]
	v_pk_mul_f32 v[54:55], v[212:213], 0 op_sel_hi:[1,0]
	v_mfma_f32_32x32x16_bf16 v[82:97], v[62:65], v[118:121], v[82:97]
	v_mul_f32_e64 v64, v60, 0
	v_mul_f32_e64 v65, v61, 0
	v_mul_f32_e64 v60, v52, 0
	v_mul_f32_e64 v61, v53, 0
	v_mul_f32_e64 v52, v210, 0
	v_mul_f32_e64 v53, v211, 0
	v_pk_mul_f32 v[62:63], v[58:59], 0 op_sel_hi:[1,0]
	v_pk_mul_f32 v[58:59], v[50:51], 0 op_sel_hi:[1,0]
	v_pk_mul_f32 v[50:51], v[208:209], 0 op_sel_hi:[1,0]
	v_mfma_f32_32x32x16_bf16 v[66:81], v[114:117], v[118:121], v[66:81]
	ds_read_b128 v[114:117], v199 offset:24576
	ds_read_b128 v[118:121], v199 offset:28672
	ds_read_b128 v[208:211], v232 offset:24576
	ds_read_b128 v[212:215], v232 offset:28672
	ds_read_b128 v[216:219], v233 offset:24576
	ds_read_b128 v[220:223], v233 offset:28672
	ds_read_b128 v[224:227], v234 offset:24576
	ds_read_b128 v[228:231], v234 offset:28672
	v_mfma_f32_32x32x16_bf16 v[82:97], v[122:125], v[110:113], v[82:97]
	v_mfma_f32_32x32x16_bf16 v[66:81], v[126:129], v[110:113], v[66:81]
	v_mfma_f32_32x32x16_bf16 v[82:97], v[130:133], v[106:109], v[82:97]
	v_mfma_f32_32x32x16_bf16 v[66:81], v[182:185], v[106:109], v[66:81]
	v_mfma_f32_32x32x16_bf16 v[82:97], v[186:189], v[102:105], v[82:97]
	v_mfma_f32_32x32x16_bf16 v[66:81], v[190:193], v[102:105], v[66:81]
	v_mfma_f32_32x32x16_bf16 v[82:97], v[194:197], v[98:101], v[82:97]
	v_mfma_f32_32x32x16_bf16 v[66:81], v[204:207], v[98:101], v[66:81]
	ds_read_b128 v[122:125], v199 offset:32768
	ds_read_b128 v[126:129], v199 offset:36864
	ds_read_b128 v[130:133], v232 offset:32768
	ds_read_b128 v[182:185], v232 offset:36864
	ds_read_b128 v[186:189], v233 offset:32768
	ds_read_b128 v[190:193], v233 offset:36864
	ds_read_b128 v[194:197], v234 offset:32768
	ds_read_b128 v[204:207], v234 offset:36864
	s_waitcnt lgkmcnt(0)
	v_mfma_f32_32x32x16_bf16 v[2:17], v[114:117], v[110:113], v[2:17]
	v_mfma_f32_32x32x16_bf16 v[18:33], v[118:121], v[110:113], v[18:33]
	v_mfma_f32_32x32x16_bf16 v[2:17], v[208:211], v[106:109], v[2:17]
	v_mfma_f32_32x32x16_bf16 v[18:33], v[212:215], v[106:109], v[18:33]
	v_mfma_f32_32x32x16_bf16 v[2:17], v[216:219], v[102:105], v[2:17]
	v_mfma_f32_32x32x16_bf16 v[18:33], v[220:223], v[102:105], v[18:33]
	v_mfma_f32_32x32x16_bf16 v[2:17], v[224:227], v[98:101], v[2:17]
	v_mfma_f32_32x32x16_bf16 v[18:33], v[228:231], v[98:101], v[18:33]
	s_or_b64 s[22:23], s[20:21], s[12:13]
	v_cndmask_b32_e64 v114, v82, v83, s[0:1]
	s_or_b32 s8, s22, 32
	v_mfma_f32_32x32x16_bf16 v[34:49], v[122:125], v[110:113], v[34:49]
	v_mov_b32_dpp v114, v114 quad_perm:[1,0,3,2] row_mask:0xf bank_mask:0xf bound_ctrl:1
	v_cndmask_b32_e64 v83, v83, v114, s[0:1]
	v_cndmask_b32_e64 v82, v114, v82, s[0:1]
	v_cvt_pk_bf16_f32 v114, v82, v83
	v_mov_b32_e32 v83, s23
	v_or_b32_e32 v82, s22, v136
	v_lshlrev_b64 v[82:83], 11, v[82:83]
	v_lshl_add_u64 v[82:83], v[158:159], 0, v[82:83]
	global_store_dword v[82:83], v114, off
	v_mov_b32_e32 v82, v84
	v_mfma_f32_32x32x16_bf16 v[50:65], v[126:129], v[110:113], v[50:65]
	v_cndmask_b32_e64 v83, v82, v85, s[0:1]
	s_mov_b32 s82, 2
	s_nop 0
	v_mov_b32_dpp v83, v83 quad_perm:[1,0,3,2] row_mask:0xf bank_mask:0xf bound_ctrl:1
	v_cndmask_b32_e64 v84, v85, v83, s[0:1]
	v_cndmask_b32_e64 v82, v83, v82, s[0:1]
	v_cvt_pk_bf16_f32 v84, v82, v84
	v_mov_b32_e32 v83, s23
	v_or_b32_e32 v82, s22, v138
	v_lshlrev_b64 v[82:83], 11, v[82:83]
	v_lshl_add_u64 v[82:83], v[158:159], 0, v[82:83]
	global_store_dword v[82:83], v84, off
	v_mov_b32_e32 v82, v87
	v_mfma_f32_32x32x16_bf16 v[34:49], v[130:133], v[106:109], v[34:49]
	v_cndmask_b32_e64 v83, v86, v82, s[0:1]
	s_nop 1
	v_mov_b32_dpp v83, v83 quad_perm:[1,0,3,2] row_mask:0xf bank_mask:0xf bound_ctrl:1
	v_cndmask_b32_e64 v82, v82, v83, s[0:1]
	v_cndmask_b32_e64 v83, v83, v86, s[0:1]
	v_cvt_pk_bf16_f32 v84, v83, v82
	v_mov_b32_e32 v83, s23
	v_or_b32_e32 v82, s22, v140
	v_lshlrev_b64 v[82:83], 11, v[82:83]
	v_lshl_add_u64 v[82:83], v[158:159], 0, v[82:83]
	global_store_dword v[82:83], v84, off
	v_mov_b32_e32 v82, v88
	v_mfma_f32_32x32x16_bf16 v[50:65], v[182:185], v[106:109], v[50:65]
	v_cndmask_b32_e64 v83, v82, v89, s[0:1]
	s_nop 1
	v_mov_b32_dpp v83, v83 quad_perm:[1,0,3,2] row_mask:0xf bank_mask:0xf bound_ctrl:1
	v_cndmask_b32_e64 v84, v89, v83, s[0:1]
	v_cndmask_b32_e64 v82, v83, v82, s[0:1]
	v_cvt_pk_bf16_f32 v84, v82, v84
	v_mov_b32_e32 v83, s23
	v_or_b32_e32 v82, s22, v142
	v_lshlrev_b64 v[82:83], 11, v[82:83]
	v_lshl_add_u64 v[82:83], v[158:159], 0, v[82:83]
	global_store_dword v[82:83], v84, off
	v_mov_b32_e32 v82, v90
	v_mfma_f32_32x32x16_bf16 v[34:49], v[186:189], v[102:105], v[34:49]
	v_cndmask_b32_e64 v83, v82, v91, s[0:1]
	s_nop 1
	v_mov_b32_dpp v83, v83 quad_perm:[1,0,3,2] row_mask:0xf bank_mask:0xf bound_ctrl:1
	v_cndmask_b32_e64 v84, v91, v83, s[0:1]
	v_cndmask_b32_e64 v82, v83, v82, s[0:1]
	v_cvt_pk_bf16_f32 v84, v82, v84
	v_mov_b32_e32 v83, s23
	v_or_b32_e32 v82, s22, v144
	v_lshlrev_b64 v[82:83], 11, v[82:83]
	v_lshl_add_u64 v[82:83], v[158:159], 0, v[82:83]
	global_store_dword v[82:83], v84, off
	v_mov_b32_e32 v82, v93
	v_mfma_f32_32x32x16_bf16 v[50:65], v[190:193], v[102:105], v[50:65]
	v_cndmask_b32_e64 v83, v92, v82, s[0:1]
	s_nop 1
	v_mov_b32_dpp v83, v83 quad_perm:[1,0,3,2] row_mask:0xf bank_mask:0xf bound_ctrl:1
	v_cndmask_b32_e64 v82, v82, v83, s[0:1]
	v_cndmask_b32_e64 v83, v83, v92, s[0:1]
	v_cvt_pk_bf16_f32 v84, v83, v82
	v_mov_b32_e32 v83, s23
	v_or_b32_e32 v82, s22, v148
	v_lshlrev_b64 v[82:83], 11, v[82:83]
	v_lshl_add_u64 v[82:83], v[158:159], 0, v[82:83]
; DI int crow(int r, int hi) { return (r & 3) + 8 * (r >> 2) + 4 * hi; }
; DI unsigned pkbf(float a, float b) { f32x2 v = {a, b}; bfx2 r = __builtin_convertvector(v, bfx2); return __builtin_bit_cast(unsigned, r); }
; DI void phase_gla_chain(const Params& P, int l, int task0, int ntask_stride, LAS unsigned char* lds) {
;     ...
;             { const int cs = dir ? 63 - n : n; const size_t tokb = (size_t)sq * SEQL + cs * 64; const int odd = lane & 1;
;               bf16_t* ob = OFB + (size_t)dir * MTOK * 1024 + h * 256 + wid * 32 + (r32 & ~1);
; #pragma unroll
;               for (int ib = 0; ib < 2; ++ib)
; #pragma unroll
;                   for (int x = 0; x < 16; x += 2) { float ea_ = o[ib][x], eb_ = o[ib][x + 1]; asm volatile("" : "+v"(ea_), "+v"(eb_)); const float mine = odd ? eb_ : ea_, give = odd ? ea_ : eb_;
;                       const float got = __int_as_float(__builtin_amdgcn_update_dpp(0, __float_as_int(give), 0xB1, 0xF, 0xF, true));
;                       const unsigned w = odd ? pkbf(got, mine) : pkbf(mine, got);
;                       *(unsigned*)(ob + (tokb + ib * 32 + crow(x + odd, hi)) * 1024) = w; } }
	global_store_dword v[82:83], v84, off
	v_mov_b32_e32 v82, v94
	v_mfma_f32_32x32x16_bf16 v[34:49], v[194:197], v[98:101], v[34:49]
	v_cndmask_b32_e64 v83, v82, v95, s[0:1]
	s_nop 1
	v_mov_b32_dpp v83, v83 quad_perm:[1,0,3,2] row_mask:0xf bank_mask:0xf bound_ctrl:1
	v_cndmask_b32_e64 v84, v95, v83, s[0:1]
	v_cndmask_b32_e64 v82, v83, v82, s[0:1]
	v_cvt_pk_bf16_f32 v84, v82, v84
	v_mov_b32_e32 v83, s23
	v_or_b32_e32 v82, s22, v150
	v_lshlrev_b64 v[82:83], 11, v[82:83]
	v_lshl_add_u64 v[82:83], v[158:159], 0, v[82:83]
	global_store_dword v[82:83], v84, off
	v_mov_b32_e32 v82, v96
	v_mfma_f32_32x32x16_bf16 v[50:65], v[204:207], v[98:101], v[50:65]
	v_cndmask_b32_e64 v83, v82, v97, s[0:1]
	s_nop 1
	v_mov_b32_dpp v83, v83 quad_perm:[1,0,3,2] row_mask:0xf bank_mask:0xf bound_ctrl:1
	v_cndmask_b32_e64 v84, v97, v83, s[0:1]
	v_cndmask_b32_e64 v82, v83, v82, s[0:1]
	v_cvt_pk_bf16_f32 v84, v82, v84
	v_mov_b32_e32 v83, s23
	v_or_b32_e32 v82, s22, v152
	v_lshlrev_b64 v[82:83], 11, v[82:83]
	v_lshl_add_u64 v[82:83], v[158:159], 0, v[82:83]
	global_store_dword v[82:83], v84, off
	s_nop 0
	v_cndmask_b32_e64 v82, v66, v67, s[0:1]
	s_nop 1
	v_mov_b32_dpp v82, v82 quad_perm:[1,0,3,2] row_mask:0xf bank_mask:0xf bound_ctrl:1
	v_cndmask_b32_e64 v67, v67, v82, s[0:1]
	v_cndmask_b32_e64 v66, v82, v66, s[0:1]
	v_cvt_pk_bf16_f32 v82, v66, v67
	v_mov_b32_e32 v67, s23
	v_or_b32_e32 v66, s8, v136
	v_lshlrev_b64 v[66:67], 11, v[66:67]
	v_lshl_add_u64 v[66:67], v[158:159], 0, v[66:67]
	global_store_dword v[66:67], v82, off
	v_mov_b32_e32 v66, v69
	s_nop 0
	v_cndmask_b32_e64 v67, v68, v66, s[0:1]
	s_nop 1
	v_mov_b32_dpp v67, v67 quad_perm:[1,0,3,2] row_mask:0xf bank_mask:0xf bound_ctrl:1
	v_cndmask_b32_e64 v66, v66, v67, s[0:1]
	v_cndmask_b32_e64 v67, v67, v68, s[0:1]
	v_cvt_pk_bf16_f32 v68, v67, v66
	v_mov_b32_e32 v67, s23
	v_or_b32_e32 v66, s8, v138
	v_lshlrev_b64 v[66:67], 11, v[66:67]
	v_lshl_add_u64 v[66:67], v[158:159], 0, v[66:67]
	global_store_dword v[66:67], v68, off
	v_mov_b32_e32 v66, v70
	s_nop 0
	v_cndmask_b32_e64 v67, v66, v71, s[0:1]
	s_nop 1
	v_mov_b32_dpp v67, v67 quad_perm:[1,0,3,2] row_mask:0xf bank_mask:0xf bound_ctrl:1
	v_cndmask_b32_e64 v68, v71, v67, s[0:1]
	v_cndmask_b32_e64 v66, v67, v66, s[0:1]
	v_cvt_pk_bf16_f32 v68, v66, v68
	v_mov_b32_e32 v67, s23
	v_or_b32_e32 v66, s8, v140
	v_lshlrev_b64 v[66:67], 11, v[66:67]
	v_lshl_add_u64 v[66:67], v[158:159], 0, v[66:67]
	global_store_dword v[66:67], v68, off
	v_mov_b32_e32 v66, v73
	s_nop 0
	v_cndmask_b32_e64 v67, v72, v66, s[0:1]
	s_nop 1
	v_mov_b32_dpp v67, v67 quad_perm:[1,0,3,2] row_mask:0xf bank_mask:0xf bound_ctrl:1
	v_cndmask_b32_e64 v66, v66, v67, s[0:1]
	v_cndmask_b32_e64 v67, v67, v72, s[0:1]
	v_cvt_pk_bf16_f32 v68, v67, v66
	v_mov_b32_e32 v67, s23
	v_or_b32_e32 v66, s8, v142
	v_lshlrev_b64 v[66:67], 11, v[66:67]
	v_lshl_add_u64 v[66:67], v[158:159], 0, v[66:67]
	global_store_dword v[66:67], v68, off
	v_mov_b32_e32 v66, v75
	s_nop 0
	v_cndmask_b32_e64 v67, v74, v66, s[0:1]
	s_nop 1
	v_mov_b32_dpp v67, v67 quad_perm:[1,0,3,2] row_mask:0xf bank_mask:0xf bound_ctrl:1
	v_cndmask_b32_e64 v66, v66, v67, s[0:1]
	v_cndmask_b32_e64 v67, v67, v74, s[0:1]
	v_cvt_pk_bf16_f32 v68, v67, v66
	v_mov_b32_e32 v67, s23
	v_or_b32_e32 v66, s8, v144
	v_lshlrev_b64 v[66:67], 11, v[66:67]
	v_lshl_add_u64 v[66:67], v[158:159], 0, v[66:67]
	global_store_dword v[66:67], v68, off
	v_mov_b32_e32 v66, v76
	s_nop 0
	v_cndmask_b32_e64 v67, v66, v77, s[0:1]
	s_nop 1
	v_mov_b32_dpp v67, v67 quad_perm:[1,0,3,2] row_mask:0xf bank_mask:0xf bound_ctrl:1
	v_cndmask_b32_e64 v68, v77, v67, s[0:1]
	v_cndmask_b32_e64 v66, v67, v66, s[0:1]
	v_cvt_pk_bf16_f32 v68, v66, v68
	v_mov_b32_e32 v67, s23
	v_or_b32_e32 v66, s8, v148
	v_lshlrev_b64 v[66:67], 11, v[66:67]
	v_lshl_add_u64 v[66:67], v[158:159], 0, v[66:67]
	global_store_dword v[66:67], v68, off
	v_mov_b32_e32 v66, v78
	s_nop 0
	v_cndmask_b32_e64 v67, v66, v79, s[0:1]
	s_nop 1
	v_mov_b32_dpp v67, v67 quad_perm:[1,0,3,2] row_mask:0xf bank_mask:0xf bound_ctrl:1
	v_cndmask_b32_e64 v68, v79, v67, s[0:1]
	v_cndmask_b32_e64 v66, v67, v66, s[0:1]
	v_cvt_pk_bf16_f32 v68, v66, v68
	v_mov_b32_e32 v67, s23
	v_or_b32_e32 v66, s8, v150
	v_lshlrev_b64 v[66:67], 11, v[66:67]
	v_lshl_add_u64 v[66:67], v[158:159], 0, v[66:67]
	global_store_dword v[66:67], v68, off
	v_mov_b32_e32 v66, v81
	s_nop 0
	v_cndmask_b32_e64 v67, v80, v66, s[0:1]
	s_nop 1
	v_mov_b32_dpp v67, v67 quad_perm:[1,0,3,2] row_mask:0xf bank_mask:0xf bound_ctrl:1
	v_cndmask_b32_e64 v66, v66, v67, s[0:1]
	v_cndmask_b32_e64 v67, v67, v80, s[0:1]
	v_cvt_pk_bf16_f32 v68, v67, v66
	v_mov_b32_e32 v67, s23
	v_or_b32_e32 v66, s8, v152
	v_lshlrev_b64 v[66:67], 11, v[66:67]
	v_lshl_add_u64 v[66:67], v[158:159], 0, v[66:67]
	s_mov_b32 s8, 61
	global_store_dword v[66:67], v68, off
	s_cmp_lt_i32 s8, 0
	s_cbranch_scc1 .Lvt_p_1
	s_and_b64 s[88:89], s[10:11], exec
	s_cselect_b32 s88, s82, s8
	s_add_i32 s88, s88, s81
	s_lshl_b32 s88, s88, 2
	s_or_b32 s88, s88, s80
	s_ashr_i32 s89, s88, 31
	s_lshl_b64 s[88:89], s[88:89], 15
	s_add_u32 s88, s29, s88
	s_addc_u32 s89, s30, s89
	s_lshl_b32 s90, s31, 4
	s_add_u32 s88, s88, s90
	s_addc_u32 s89, s89, 0
	s_add_i32 s91, s82, -1
	s_and_b32 s91, s91, 1
	s_xor_b32 s91, s91, 1
	s_mul_i32 s91, s91, 0x12400
	s_add_i32 s91, s91, s90
	s_add_i32 m0, s91, 0xa000
	s_nop 0
	global_load_lds_dwordx4 v134, s[88:89] nt
	global_load_lds_dwordx4 v134, s[88:89] offset:1024 nt
	global_load_lds_dwordx4 v134, s[88:89] offset:2048 nt
	global_load_lds_dwordx4 v134, s[88:89] offset:3072 nt

; #define LAS __attribute__((address_space(3)))
; #define RD_QD(dst, s0) _Pragma("unroll") for (int s_ = 0; s_ < 4; ++s_) { dst[s_] = *(const LAS bf16x8*)(B + CH_QD + i0 * 256 + (((2 * ((s0) + s_) + hi) ^ (i0 & 15)) << 4)); \
;                 dst[4 + s_] = *(const LAS bf16x8*)(B + CH_QD + i1 * 256 + (((2 * ((s0) + s_) + hi) ^ (i1 & 15)) << 4)); }
; #define DECAY(db_) do { f32x4 dc_[4]; _Pragma("unroll") for (int a4_ = 0; a4_ < 4; ++a4_) dc_[a4_] = *(const LAS f32x4*)(B + CH_DEC + ((db_) * 32 + 8 * a4_ + 4 * hi) * 4); \
;                 _Pragma("unroll") for (int a4_ = 0; a4_ < 4; ++a4_) _Pragma("unroll") for (int b4_ = 0; b4_ < 4; ++b4_) T[db_][a4_ * 4 + b4_] *= dc_[a4_][b4_]; } while (0)
; DI void phase_gla_chain(const Params& P, int l, int task0, int ntask_stride, LAS unsigned char* lds) {
;     ...
;             const int i0 = r32, i1 = 32 + r32; const int vv = wid * 32 + r32;
;             bf16x8 fa[8], fb[8], vf[4];
;             f32x16 o[2]; for (int x = 0; x < 16; ++x) { o[0][x] = 0.f; o[1][x] = 0.f; }
;     ...
;             RD_QD(fa, 0);
; #pragma unroll
;             for (int ks = 0; ks < 4; ++ks) vf[ks] = *(const LAS bf16x8*)(B + CH_VT + vv * 128 + (((2 * ks + hi) ^ ((vv >> 1) & 7)) << 4));
;             __builtin_amdgcn_sched_barrier(0);
;             RD_QD(fb, 4);
;             __builtin_amdgcn_sched_barrier(0);
;             MM_QD(fa, 0);
;             DECAY(0); DECAY(1);
;             __builtin_amdgcn_sched_barrier(0);
; #pragma unroll
;             for (int ks = 0; ks < 4; ++ks) { fa[ks] = *(const LAS bf16x8*)(B + CH_AM + i0 * 128 + (((2 * ks + hi) ^ ((i0 >> 1) & 7)) << 4)); fa[4 + ks] = *(const LAS bf16x8*)(B + CH_AM + i1 * 128 + (((2 * ks + hi) ^ ((i1 >> 1) & 7)) << 4)); }
;             __builtin_amdgcn_sched_barrier(0);
;             MM_QD(fb, 4);
;             DECAY(2); DECAY(3);
;             __builtin_amdgcn_sched_barrier(0);
.LBB0_971:
	s_mul_i32 s84, s84, 0x12400
	s_add_i32 s22, s84, 0
	v_add_u32_e32 v74, s22, v201
	v_add_u32_e32 v75, s22, v141
	v_add_u32_e32 v66, v74, v149
	v_add_u32_e32 v70, v75, v149
	v_add_u32_e32 v76, v74, v151
	ds_read_b128 v[66:69], v66
	ds_read_b128 v[70:73], v70
	v_add_u32_e32 v77, v75, v151
	ds_read_b128 v[182:185], v76
	ds_read_b128 v[186:189], v77
	v_add_u32_e32 v76, v74, v153
	v_add_u32_e32 v77, v75, v153
	ds_read_b128 v[190:193], v76
	ds_read_b128 v[194:197], v77
	v_add_u32_e32 v76, v74, v160
	v_add_u32_e32 v77, v75, v160
	ds_read_b128 v[204:207], v76
	ds_read_b128 v[208:211], v77
	v_add_u32_e32 v76, s22, v173
	v_add_u32_e32 v77, v76, v162
	v_add_u32_e32 v78, v76, v164
	ds_read_b128 v[110:113], v77 offset:40960
	ds_read_b128 v[106:109], v78 offset:40960
	v_add_u32_e32 v77, v76, v165
	v_add_u32_e32 v76, v76, v166
	ds_read_b128 v[102:105], v77 offset:40960
	ds_read_b128 v[98:101], v76 offset:40960
	v_add_u32_e32 v76, v74, v167
	v_add_u32_e32 v77, v75, v167
	ds_read_b128 v[212:215], v76
	ds_read_b128 v[216:219], v77
	v_add_u32_e32 v76, v74, v168
	v_add_u32_e32 v77, v75, v168
	ds_read_b128 v[220:223], v76
	ds_read_b128 v[130:133], v77
	v_add_u32_e32 v76, v74, v169
	v_add_u32_e32 v74, v74, v170
	v_add_u32_e32 v77, v75, v169
	ds_read_b128 v[126:129], v76
	ds_read_b128 v[122:125], v77
	v_add_u32_e32 v75, v75, v170
	ds_read_b128 v[118:121], v74
	ds_read_b128 v[114:117], v75
	v_cvt_pk_bf16_f32 v74, v2, v3
	v_cvt_pk_bf16_f32 v75, v4, v5
	v_cvt_pk_bf16_f32 v76, v6, v7
	v_cvt_pk_bf16_f32 v77, v8, v9
	v_cvt_pk_bf16_f32 v224, v10, v11
	v_cvt_pk_bf16_f32 v225, v12, v13
	s_waitcnt lgkmcnt(0)
	v_mfma_f32_32x32x16_bf16 v[82:97], v[66:69], v[74:77], 0
	v_cvt_pk_bf16_f32 v226, v14, v15
	v_cvt_pk_bf16_f32 v227, v16, v17
	v_add_u32_e32 v198, s22, v146
	v_add_u32_e32 v199, 0x12000, v198
	v_cvt_pk_bf16_f32 v228, v26, v27
	v_cvt_pk_bf16_f32 v229, v28, v29
	v_cvt_pk_bf16_f32 v230, v30, v31
	v_mfma_f32_32x32x16_bf16 v[66:81], v[70:73], v[74:77], 0
	v_cvt_pk_bf16_f32 v231, v32, v33
	v_mfma_f32_32x32x16_bf16 v[82:97], v[182:185], v[224:227], v[82:97]
	v_cvt_pk_bf16_f32 v182, v18, v19
	v_cvt_pk_bf16_f32 v183, v20, v21
	v_cvt_pk_bf16_f32 v184, v22, v23
	v_cvt_pk_bf16_f32 v185, v24, v25
	v_mfma_f32_32x32x16_bf16 v[66:81], v[186:189], v[224:227], v[66:81]
	ds_read_b128 v[186:189], v199 offset:64
	ds_read_b128 v[224:227], v199 offset:96
	ds_read_b128 v[232:235], v199
	ds_read_b128 v[236:239], v199 offset:32
	s_waitcnt lgkmcnt(0)
	v_pk_mul_f32 v[10:11], v[10:11], v[186:187]
	v_pk_mul_f32 v[12:13], v[12:13], v[188:189]
	v_pk_mul_f32 v[14:15], v[14:15], v[224:225]
	v_pk_mul_f32 v[6:7], v[6:7], v[236:237]
	v_pk_mul_f32 v[16:17], v[16:17], v[226:227]
	v_mfma_f32_32x32x16_bf16 v[82:97], v[190:193], v[182:185], v[82:97]
	v_mul_f32_e64 v8, v8, v238
	v_mul_f32_e64 v9, v9, v239
	v_mul_f32_e64 v4, v4, v234
	v_mul_f32_e64 v5, v5, v235
	v_mul_f32_e64 v2, v2, v232
	v_mul_f32_e64 v3, v3, v233
	v_mfma_f32_32x32x16_bf16 v[66:81], v[194:197], v[182:185], v[66:81]
	v_add_u32_e32 v194, 0x12080, v198
	ds_read_b128 v[182:185], v194 offset:64
	ds_read_b128 v[186:189], v194 offset:96
	ds_read_b128 v[190:193], v194
	ds_read_b128 v[194:197], v194 offset:32
	s_waitcnt lgkmcnt(0)
	v_pk_mul_f32 v[26:27], v[26:27], v[182:183]
	v_pk_mul_f32 v[30:31], v[30:31], v[186:187]
	v_pk_mul_f32 v[32:33], v[32:33], v[188:189]
	v_pk_mul_f32 v[22:23], v[22:23], v[194:195]
	v_pk_mul_f32 v[28:29], v[28:29], v[184:185]
	v_pk_mul_f32 v[24:25], v[24:25], v[196:197]
	v_pk_mul_f32 v[20:21], v[20:21], v[192:193]
	v_pk_mul_f32 v[18:19], v[18:19], v[190:191]
	v_mfma_f32_32x32x16_bf16 v[82:97], v[204:207], v[228:231], v[82:97]
	v_mfma_f32_32x32x16_bf16 v[66:81], v[208:211], v[228:231], v[66:81]
	v_add_u32_e32 v199, s22, v143
	v_add_u32_e32 v224, s22, v145
	v_add_u32_e32 v240, v199, v162
	v_add_u32_e32 v186, v224, v162
	v_add_u32_e32 v241, v199, v164
	v_add_u32_e32 v194, v224, v164
	v_add_u32_e32 v242, v199, v165
	v_add_u32_e32 v208, v224, v165
	v_add_u32_e32 v199, v199, v166
	v_add_u32_e32 v228, v224, v166
	ds_read_b128 v[182:185], v240 offset:16384
	ds_read_b128 v[186:189], v186 offset:16384
	ds_read_b128 v[190:193], v241 offset:16384
	ds_read_b128 v[194:197], v194 offset:16384
	ds_read_b128 v[204:207], v242 offset:16384
	ds_read_b128 v[208:211], v208 offset:16384
	ds_read_b128 v[224:227], v199 offset:16384
	ds_read_b128 v[228:231], v228 offset:16384
	v_cvt_pk_bf16_f32 v232, v34, v35
	v_cvt_pk_bf16_f32 v233, v36, v37
	v_cvt_pk_bf16_f32 v234, v38, v39
	v_cvt_pk_bf16_f32 v235, v40, v41
	s_nop 1
	v_mfma_f32_32x32x16_bf16 v[82:97], v[212:215], v[232:235], v[82:97]
	v_cvt_pk_bf16_f32 v212, v42, v43
	v_cvt_pk_bf16_f32 v213, v44, v45
	v_cvt_pk_bf16_f32 v214, v46, v47
	v_cvt_pk_bf16_f32 v215, v48, v49
	v_mfma_f32_32x32x16_bf16 v[66:81], v[216:219], v[232:235], v[66:81]
	v_cvt_pk_bf16_f32 v216, v50, v51
	v_cvt_pk_bf16_f32 v217, v52, v53
	v_cvt_pk_bf16_f32 v218, v54, v55
	v_cvt_pk_bf16_f32 v219, v56, v57
	v_mfma_f32_32x32x16_bf16 v[82:97], v[220:223], v[212:215], v[82:97]
	v_add_u32_e32 v223, 0x12100, v198
	v_add_u32_e32 v198, 0x12180, v198
	v_cvt_pk_bf16_f32 v220, v58, v59
	v_cvt_pk_bf16_f32 v221, v60, v61
	v_cvt_pk_bf16_f32 v222, v62, v63
	v_mfma_f32_32x32x16_bf16 v[66:81], v[130:133], v[212:215], v[66:81]
	ds_read_b128 v[130:133], v223 offset:64
	ds_read_b128 v[212:215], v223 offset:96
	ds_read_b128 v[232:235], v223
	ds_read_b128 v[236:239], v223 offset:32
	v_cvt_pk_bf16_f32 v223, v64, v65
	s_waitcnt lgkmcnt(0)
; #define LAS __attribute__((address_space(3)))
; DI int crow(int r, int hi) { return (r & 3) + 8 * (r >> 2) + 4 * hi; }
; DI unsigned pkbf(float a, float b) { f32x2 v = {a, b}; bfx2 r = __builtin_convertvector(v, bfx2); return __builtin_bit_cast(unsigned, r); }
; #define MM_KT(src, db0) _Pragma("unroll") for (int q_ = 0; q_ < 2; ++q_) { \
;                 _Pragma("unroll") for (int ks_ = 0; ks_ < 4; ++ks_) T[(db0) + q_] = __builtin_amdgcn_mfma_f32_32x32x16_bf16(src[q_ * 4 + ks_], vf[ks_], T[(db0) + q_], 0, 0, 0); }
; DI void phase_gla_chain(const Params& P, int l, int task0, int ntask_stride, LAS unsigned char* lds) {
;     ...
;             for (int ks = 0; ks < 4; ++ks) { fa[ks] = *(const LAS bf16x8*)(B + CH_AM + i0 * 128 + (((2 * ks + hi) ^ ((i0 >> 1) & 7)) << 4)); fa[4 + ks] = *(const LAS bf16x8*)(B + CH_AM + i1 * 128 + (((2 * ks + hi) ^ ((i1 >> 1) & 7)) << 4)); }
;             __builtin_amdgcn_sched_barrier(0);
;             MM_QD(fb, 4);
;             DECAY(2); DECAY(3);
;             __builtin_amdgcn_sched_barrier(0);
;             RD_KT(fb, 0);
;             __builtin_amdgcn_sched_barrier(0);
; #pragma unroll
;             for (int ks = 0; ks < 4; ++ks) { o[0] = __builtin_amdgcn_mfma_f32_32x32x16_bf16(fa[ks], vf[ks], o[0], 0, 0, 0); o[1] = __builtin_amdgcn_mfma_f32_32x32x16_bf16(fa[4 + ks], vf[ks], o[1], 0, 0, 0); }
;             __builtin_amdgcn_sched_barrier(0);
;             RD_KT(fa, 2);
;             __builtin_amdgcn_sched_barrier(0);
;             MM_KT(fb, 0);
;             __builtin_amdgcn_sched_barrier(0);
;             MM_KT(fa, 2);
;     ...
;             { const int cs = dir ? 63 - n : n; const size_t tokb = (size_t)sq * SEQL + cs * 64; const int odd = lane & 1;
;               bf16_t* ob = OFB + (size_t)dir * MTOK * 1024 + h * 256 + wid * 32 + (r32 & ~1);
; #pragma unroll
;               for (int ib = 0; ib < 2; ++ib)
; #pragma unroll
;                   for (int x = 0; x < 16; x += 2) { float ea_ = o[ib][x], eb_ = o[ib][x + 1]; asm volatile("" : "+v"(ea_), "+v"(eb_)); const float mine = odd ? eb_ : ea_, give = odd ? ea_ : eb_;
;                       const float got = __int_as_float(__builtin_amdgcn_update_dpp(0, __float_as_int(give), 0xB1, 0xF, 0xF, true));
;                       const unsigned w = odd ? pkbf(got, mine) : pkbf(mine, got);
;                       *(unsigned*)(ob + (tokb + ib * 32 + crow(x + odd, hi)) * 1024) = w; } }
	v_pk_mul_f32 v[42:43], v[42:43], v[130:131]
	v_pk_mul_f32 v[46:47], v[46:47], v[212:213]
	v_pk_mul_f32 v[48:49], v[48:49], v[214:215]
	v_pk_mul_f32 v[44:45], v[44:45], v[132:133]
	v_pk_mul_f32 v[38:39], v[38:39], v[236:237]
	v_mfma_f32_32x32x16_bf16 v[82:97], v[126:129], v[216:219], v[82:97]
	v_mul_f32_e64 v40, v40, v238
	v_mul_f32_e64 v41, v41, v239
	v_mul_f32_e64 v36, v36, v234
	v_mul_f32_e64 v37, v37, v235
	v_mul_f32_e64 v34, v34, v232
	v_mul_f32_e64 v35, v35, v233
	v_mfma_f32_32x32x16_bf16 v[66:81], v[122:125], v[216:219], v[66:81]
	ds_read_b128 v[122:125], v198 offset:64
	ds_read_b128 v[126:129], v198 offset:96
	ds_read_b128 v[130:133], v198
	ds_read_b128 v[212:215], v198 offset:32
	s_waitcnt lgkmcnt(0)
	v_pk_mul_f32 v[58:59], v[58:59], v[122:123]
	v_pk_mul_f32 v[62:63], v[62:63], v[126:127]
	v_pk_mul_f32 v[64:65], v[64:65], v[128:129]
	v_pk_mul_f32 v[54:55], v[54:55], v[212:213]
	v_pk_mul_f32 v[60:61], v[60:61], v[124:125]
	v_pk_mul_f32 v[56:57], v[56:57], v[214:215]
	v_pk_mul_f32 v[52:53], v[52:53], v[132:133]
	v_pk_mul_f32 v[50:51], v[50:51], v[130:131]
	v_mfma_f32_32x32x16_bf16 v[82:97], v[118:121], v[220:223], v[82:97]
	v_mfma_f32_32x32x16_bf16 v[66:81], v[114:117], v[220:223], v[66:81]
	ds_read_b128 v[114:117], v240 offset:24576
	ds_read_b128 v[118:121], v240 offset:28672
	ds_read_b128 v[122:125], v241 offset:24576
	ds_read_b128 v[126:129], v241 offset:28672
	ds_read_b128 v[130:133], v242 offset:24576
	ds_read_b128 v[212:215], v242 offset:28672
	ds_read_b128 v[216:219], v199 offset:24576
	ds_read_b128 v[220:223], v199 offset:28672
	v_mfma_f32_32x32x16_bf16 v[82:97], v[182:185], v[110:113], v[82:97]
	v_mfma_f32_32x32x16_bf16 v[66:81], v[186:189], v[110:113], v[66:81]
	v_mfma_f32_32x32x16_bf16 v[82:97], v[190:193], v[106:109], v[82:97]
	v_mfma_f32_32x32x16_bf16 v[66:81], v[194:197], v[106:109], v[66:81]
	v_mfma_f32_32x32x16_bf16 v[82:97], v[204:207], v[102:105], v[82:97]
	v_mfma_f32_32x32x16_bf16 v[66:81], v[208:211], v[102:105], v[66:81]
	v_mfma_f32_32x32x16_bf16 v[82:97], v[224:227], v[98:101], v[82:97]
	v_mfma_f32_32x32x16_bf16 v[66:81], v[228:231], v[98:101], v[66:81]
	ds_read_b128 v[182:185], v240 offset:32768
	ds_read_b128 v[186:189], v240 offset:36864
	ds_read_b128 v[190:193], v241 offset:32768
	ds_read_b128 v[194:197], v241 offset:36864
	ds_read_b128 v[204:207], v242 offset:32768
	ds_read_b128 v[208:211], v242 offset:36864
	ds_read_b128 v[224:227], v199 offset:32768
	ds_read_b128 v[228:231], v199 offset:36864
	s_waitcnt lgkmcnt(0)
	v_mfma_f32_32x32x16_bf16 v[2:17], v[114:117], v[110:113], v[2:17]
	v_mfma_f32_32x32x16_bf16 v[18:33], v[118:121], v[110:113], v[18:33]
	v_mfma_f32_32x32x16_bf16 v[2:17], v[122:125], v[106:109], v[2:17]
	v_mfma_f32_32x32x16_bf16 v[18:33], v[126:129], v[106:109], v[18:33]
	v_mfma_f32_32x32x16_bf16 v[2:17], v[130:133], v[102:105], v[2:17]
	v_mfma_f32_32x32x16_bf16 v[18:33], v[212:215], v[102:105], v[18:33]
	v_mfma_f32_32x32x16_bf16 v[2:17], v[216:219], v[98:101], v[2:17]
	v_mfma_f32_32x32x16_bf16 v[18:33], v[220:223], v[98:101], v[18:33]
	s_add_i32 s64, s8, 1
	s_and_b64 s[22:23], s[10:11], exec
	s_cselect_b32 s22, s83, s64
	s_lshl_b32 s22, s22, 6
	s_add_u32 s23, s20, s22
	v_cndmask_b32_e64 v114, v82, v83, s[0:1]
	s_addc_u32 s22, s21, 0
	v_mfma_f32_32x32x16_bf16 v[34:49], v[182:185], v[110:113], v[34:49]
	v_mov_b32_dpp v114, v114 quad_perm:[1,0,3,2] row_mask:0xf bank_mask:0xf bound_ctrl:1
	v_cndmask_b32_e64 v83, v83, v114, s[0:1]
	v_cndmask_b32_e64 v82, v114, v82, s[0:1]
	v_cvt_pk_bf16_f32 v114, v82, v83
	v_readfirstlane_b32 s98, v158
	v_readfirstlane_b32 s99, v159
	v_and_b32_e32 v244, 30, v137
	v_lshlrev_b32_e32 v244, 1, v244
	v_lshl_add_u32 v244, v136, 11, v244
	s_lshl_b32 s100, s23, 11
	s_add_u32 s98, s98, s100
	s_addc_u32 s99, s99, 0
	s_add_u32 s100, s98, 0x800
	s_addc_u32 s101, s99, 0
	global_store_dword v244, v114, s[100:101] offset:-2048
	v_mov_b32_e32 v82, v84
	v_mfma_f32_32x32x16_bf16 v[50:65], v[186:189], v[110:113], v[50:65]
	v_cndmask_b32_e64 v83, v82, v85, s[0:1]
	s_add_i32 s8, s8, -1
	s_add_i32 s82, s82, 1
	v_mov_b32_dpp v83, v83 quad_perm:[1,0,3,2] row_mask:0xf bank_mask:0xf bound_ctrl:1
	v_cndmask_b32_e64 v84, v85, v83, s[0:1]
	v_cndmask_b32_e64 v82, v83, v82, s[0:1]
	v_cvt_pk_bf16_f32 v84, v82, v84
	global_store_dword v244, v84, s[100:101] offset:2048
	v_mov_b32_e32 v82, v86
	v_mfma_f32_32x32x16_bf16 v[34:49], v[190:193], v[106:109], v[34:49]
	v_cndmask_b32_e64 v83, v82, v87, s[0:1]
	s_nop 1
	v_mov_b32_dpp v83, v83 quad_perm:[1,0,3,2] row_mask:0xf bank_mask:0xf bound_ctrl:1
	v_cndmask_b32_e64 v84, v87, v83, s[0:1]
	v_cndmask_b32_e64 v82, v83, v82, s[0:1]
	v_cvt_pk_bf16_f32 v84, v82, v84
	s_add_u32 s100, s98, 0x4800
	s_addc_u32 s101, s99, 0
	global_store_dword v244, v84, s[100:101] offset:-2048
	v_mov_b32_e32 v82, v89
	v_mfma_f32_32x32x16_bf16 v[50:65], v[194:197], v[106:109], v[50:65]
	v_cndmask_b32_e64 v83, v88, v82, s[0:1]
	s_nop 1
	v_mov_b32_dpp v83, v83 quad_perm:[1,0,3,2] row_mask:0xf bank_mask:0xf bound_ctrl:1
	v_cndmask_b32_e64 v82, v82, v83, s[0:1]
	v_cndmask_b32_e64 v83, v83, v88, s[0:1]
	v_cvt_pk_bf16_f32 v84, v83, v82
	global_store_dword v244, v84, s[100:101] offset:2048
	v_mov_b32_e32 v82, v90
	v_mfma_f32_32x32x16_bf16 v[34:49], v[204:207], v[102:105], v[34:49]
; DI int crow(int r, int hi) { return (r & 3) + 8 * (r >> 2) + 4 * hi; }
; DI unsigned pkbf(float a, float b) { f32x2 v = {a, b}; bfx2 r = __builtin_convertvector(v, bfx2); return __builtin_bit_cast(unsigned, r); }
; DI void phase_gla_chain(const Params& P, int l, int task0, int ntask_stride, LAS unsigned char* lds) {
;     ...
;             { const int cs = dir ? 63 - n : n; const size_t tokb = (size_t)sq * SEQL + cs * 64; const int odd = lane & 1;
;               bf16_t* ob = OFB + (size_t)dir * MTOK * 1024 + h * 256 + wid * 32 + (r32 & ~1);
; #pragma unroll
;               for (int ib = 0; ib < 2; ++ib)
; #pragma unroll
;                   for (int x = 0; x < 16; x += 2) { float ea_ = o[ib][x], eb_ = o[ib][x + 1]; asm volatile("" : "+v"(ea_), "+v"(eb_)); const float mine = odd ? eb_ : ea_, give = odd ? ea_ : eb_;
;                       const float got = __int_as_float(__builtin_amdgcn_update_dpp(0, __float_as_int(give), 0xB1, 0xF, 0xF, true));
;                       const unsigned w = odd ? pkbf(got, mine) : pkbf(mine, got);
;                       *(unsigned*)(ob + (tokb + ib * 32 + crow(x + odd, hi)) * 1024) = w; } }
	v_cndmask_b32_e64 v83, v82, v91, s[0:1]
	s_nop 1
	v_mov_b32_dpp v83, v83 quad_perm:[1,0,3,2] row_mask:0xf bank_mask:0xf bound_ctrl:1
	v_cndmask_b32_e64 v84, v91, v83, s[0:1]
	v_cndmask_b32_e64 v82, v83, v82, s[0:1]
	v_cvt_pk_bf16_f32 v84, v82, v84
	s_add_u32 s100, s98, 0x8800
	s_addc_u32 s101, s99, 0
	global_store_dword v244, v84, s[100:101] offset:-2048
	v_mov_b32_e32 v82, v92
	v_mfma_f32_32x32x16_bf16 v[50:65], v[208:211], v[102:105], v[50:65]
	v_cndmask_b32_e64 v83, v82, v93, s[0:1]
	s_nop 1
	v_mov_b32_dpp v83, v83 quad_perm:[1,0,3,2] row_mask:0xf bank_mask:0xf bound_ctrl:1
	v_cndmask_b32_e64 v84, v93, v83, s[0:1]
	v_cndmask_b32_e64 v82, v83, v82, s[0:1]
	v_cvt_pk_bf16_f32 v84, v82, v84
	global_store_dword v244, v84, s[100:101] offset:2048
	v_mov_b32_e32 v82, v95
	v_mfma_f32_32x32x16_bf16 v[34:49], v[224:227], v[98:101], v[34:49]
	v_cndmask_b32_e64 v83, v94, v82, s[0:1]
	s_nop 1
	v_mov_b32_dpp v83, v83 quad_perm:[1,0,3,2] row_mask:0xf bank_mask:0xf bound_ctrl:1
	v_cndmask_b32_e64 v82, v82, v83, s[0:1]
	v_cndmask_b32_e64 v83, v83, v94, s[0:1]
	v_cvt_pk_bf16_f32 v84, v83, v82
	s_add_u32 s100, s98, 0xc800
	s_addc_u32 s101, s99, 0
	global_store_dword v244, v84, s[100:101] offset:-2048
	v_mov_b32_e32 v82, v96
	v_mfma_f32_32x32x16_bf16 v[50:65], v[228:231], v[98:101], v[50:65]
	v_cndmask_b32_e64 v83, v82, v97, s[0:1]
	s_nop 1
	v_mov_b32_dpp v83, v83 quad_perm:[1,0,3,2] row_mask:0xf bank_mask:0xf bound_ctrl:1
	v_cndmask_b32_e64 v84, v97, v83, s[0:1]
	v_cndmask_b32_e64 v82, v83, v82, s[0:1]
	v_cvt_pk_bf16_f32 v84, v82, v84
	global_store_dword v244, v84, s[100:101] offset:2048
	s_or_b32 s23, s23, 32
	v_cndmask_b32_e64 v82, v66, v67, s[0:1]
	s_nop 0
	v_mov_b32_dpp v82, v82 quad_perm:[1,0,3,2] row_mask:0xf bank_mask:0xf bound_ctrl:1
	v_cndmask_b32_e64 v67, v67, v82, s[0:1]
	v_cndmask_b32_e64 v66, v82, v66, s[0:1]
	v_cvt_pk_bf16_f32 v82, v66, v67
	s_add_u32 s100, s98, 0x10800
	s_addc_u32 s101, s99, 0
	global_store_dword v244, v82, s[100:101] offset:-2048
	v_mov_b32_e32 v66, v69
	s_nop 0
	v_cndmask_b32_e64 v67, v68, v66, s[0:1]
	s_nop 1
	v_mov_b32_dpp v67, v67 quad_perm:[1,0,3,2] row_mask:0xf bank_mask:0xf bound_ctrl:1
	v_cndmask_b32_e64 v66, v66, v67, s[0:1]
	v_cndmask_b32_e64 v67, v67, v68, s[0:1]
	v_cvt_pk_bf16_f32 v68, v67, v66
	global_store_dword v244, v68, s[100:101] offset:2048
	v_mov_b32_e32 v66, v70
	s_nop 0
	v_cndmask_b32_e64 v67, v66, v71, s[0:1]
	s_nop 1
	v_mov_b32_dpp v67, v67 quad_perm:[1,0,3,2] row_mask:0xf bank_mask:0xf bound_ctrl:1
	v_cndmask_b32_e64 v68, v71, v67, s[0:1]
	v_cndmask_b32_e64 v66, v67, v66, s[0:1]
	v_cvt_pk_bf16_f32 v68, v66, v68
	s_add_u32 s100, s98, 0x14800
	s_addc_u32 s101, s99, 0
	global_store_dword v244, v68, s[100:101] offset:-2048
	v_mov_b32_e32 v66, v72
	s_nop 0
	v_cndmask_b32_e64 v67, v66, v73, s[0:1]
	s_nop 1
	v_mov_b32_dpp v67, v67 quad_perm:[1,0,3,2] row_mask:0xf bank_mask:0xf bound_ctrl:1
	v_cndmask_b32_e64 v68, v73, v67, s[0:1]
	v_cndmask_b32_e64 v66, v67, v66, s[0:1]
	v_cvt_pk_bf16_f32 v68, v66, v68
	global_store_dword v244, v68, s[100:101] offset:2048
	v_mov_b32_e32 v66, v75
	s_nop 0
	v_cndmask_b32_e64 v67, v74, v66, s[0:1]
	s_nop 1
	v_mov_b32_dpp v67, v67 quad_perm:[1,0,3,2] row_mask:0xf bank_mask:0xf bound_ctrl:1
	v_cndmask_b32_e64 v66, v66, v67, s[0:1]
	v_cndmask_b32_e64 v67, v67, v74, s[0:1]
	v_cvt_pk_bf16_f32 v68, v67, v66
	s_add_u32 s100, s98, 0x18800
	s_addc_u32 s101, s99, 0
	global_store_dword v244, v68, s[100:101] offset:-2048
	v_mov_b32_e32 v66, v77
	s_nop 0
	v_cndmask_b32_e64 v67, v76, v66, s[0:1]
	s_nop 1
	v_mov_b32_dpp v67, v67 quad_perm:[1,0,3,2] row_mask:0xf bank_mask:0xf bound_ctrl:1
	v_cndmask_b32_e64 v66, v66, v67, s[0:1]
	v_cndmask_b32_e64 v67, v67, v76, s[0:1]
	v_cvt_pk_bf16_f32 v68, v67, v66
	global_store_dword v244, v68, s[100:101] offset:2048
	v_mov_b32_e32 v66, v78
	s_nop 0
	v_cndmask_b32_e64 v67, v66, v79, s[0:1]
	s_nop 1
	v_mov_b32_dpp v67, v67 quad_perm:[1,0,3,2] row_mask:0xf bank_mask:0xf bound_ctrl:1
	v_cndmask_b32_e64 v68, v79, v67, s[0:1]
	v_cndmask_b32_e64 v66, v67, v66, s[0:1]
	v_cvt_pk_bf16_f32 v68, v66, v68
	s_add_u32 s100, s98, 0x1c800
	s_addc_u32 s101, s99, 0
	global_store_dword v244, v68, s[100:101] offset:-2048
	v_mov_b32_e32 v66, v81
	s_nop 0
	v_cndmask_b32_e64 v67, v80, v66, s[0:1]
	s_nop 1
	v_mov_b32_dpp v67, v67 quad_perm:[1,0,3,2] row_mask:0xf bank_mask:0xf bound_ctrl:1
	v_cndmask_b32_e64 v66, v66, v67, s[0:1]
	v_cndmask_b32_e64 v67, v67, v80, s[0:1]
	v_cvt_pk_bf16_f32 v68, v67, v66
	global_store_dword v244, v68, s[100:101] offset:2048
	s_cmp_lt_i32 s8, 0
	s_cbranch_scc1 .Lvt_b_1
	s_and_b64 s[88:89], s[10:11], exec
	s_cselect_b32 s88, s82, s8
	s_add_i32 s88, s88, s81
	s_lshl_b32 s88, s88, 2
	s_or_b32 s88, s88, s80
	s_ashr_i32 s89, s88, 31
	s_lshl_b64 s[88:89], s[88:89], 15
	s_add_u32 s88, s29, s88
	s_addc_u32 s89, s30, s89
	s_lshl_b32 s90, s31, 4
	s_add_u32 s88, s88, s90
	s_addc_u32 s89, s89, 0
	s_add_i32 s91, s82, -1
	s_and_b32 s91, s91, 1
	s_xor_b32 s91, s91, 1
	s_mul_i32 s91, s91, 0x12400
	s_add_i32 s91, s91, s90
	s_add_i32 m0, s91, 0xa000
	s_nop 0
	global_load_lds_dwordx4 v134, s[88:89] nt
	global_load_lds_dwordx4 v134, s[88:89] offset:1024 nt
	global_load_lds_dwordx4 v134, s[88:89] offset:2048 nt
	global_load_lds_dwordx4 v134, s[88:89] offset:3072 nt

; DI void phase_gla_chain(const Params& P, int l, int task0, int ntask_stride, LAS unsigned char* lds) {
;     ...
;         for (int n = 0; n < 64; ++n) {
;             const int b = n & 1;
;             if (n == 0) asm volatile("s_waitcnt vmcnt(0)" ::: "memory"); else asm volatile("s_waitcnt vmcnt(16)" ::: "memory");
;             __builtin_amdgcn_s_barrier();
.LBB0_972:
	s_add_i32 s83, s82, -1
	s_cmp_eq_u32 s8, -1
	s_cbranch_scc1 .Lvt_w16_1
	s_waitcnt vmcnt(20)
	s_branch .Lvt_wd_1

; DI void phase_gla_chain(const Params& P, int l, int task0, int ntask_stride, LAS unsigned char* lds) {
;     ...
;         __syncthreads();
;         CH_ISSUE(0, 0);
;         for (int n = 0; n < 64; ++n) {
;             const int b = n & 1;
;             if (n == 0) asm volatile("s_waitcnt vmcnt(0)" ::: "memory"); else asm volatile("s_waitcnt vmcnt(16)" ::: "memory");
;             __builtin_amdgcn_s_barrier();
;             asm volatile("" ::: "memory");
;             if (n + 1 < 64) CH_ISSUE(n + 1, b ^ 1);
.Lvt_wd_1:
	s_barrier
	s_and_b32 s84, s83, 1
	s_cmp_eq_u32 s8, -1
	s_cbranch_scc1 .LBB0_971
	s_and_b64 s[22:23], s[10:11], exec
	s_cselect_b32 s22, s82, s8
	s_add_i32 s22, s22, s81
	s_lshl_b32 s22, s22, 2
	s_or_b32 s86, s22, s80
	s_ashr_i32 s87, s86, 31
	s_add_u32 s22, s25, s86
	s_addc_u32 s23, 0, s87
	s_mul_i32 s64, s23, 0xa000
	s_mul_hi_u32 s65, s22, 0xa000
	s_add_i32 s65, s65, s64
	s_mul_i32 s64, s22, 0xa000
	s_add_u32 s64, s27, s64
	s_addc_u32 s65, s28, s65
	s_lshl_b64 s[86:87], s[86:87], 15
	s_add_u32 s66, s29, s86
	s_addc_u32 s67, s30, s87
	s_xor_b32 s68, s84, 1
	s_mul_i32 s68, s68, 0x12400
	s_add_i32 s85, s68, 0
	v_add_u32_e32 v245, 0x400, v134
	v_add_u32_e32 v246, 0x800, v134
	v_add_u32_e32 v247, 0xc00, v134
	v_add_u32_e32 v248, 0x1000, v134
	s_lshl_b32 s32, s31, 4
	s_lshl_b32 s98, s31, 2
	s_add_i32 s98, s98, s32
	s_add_u32 s100, s64, s98
	s_addc_u32 s101, s65, 0
	s_add_i32 s99, s85, s98
	s_add_i32 m0, s99, 0x0
	s_nop 0
	global_load_lds_dwordx4 v134, s[100:101] nt
	s_add_i32 m0, s99, 0x400
	s_nop 0
	global_load_lds_dwordx4 v245, s[100:101] nt
	s_add_i32 m0, s99, 0x800
	s_nop 0
	global_load_lds_dwordx4 v246, s[100:101] nt
	s_add_i32 m0, s99, 0xc00
	s_nop 0
	global_load_lds_dwordx4 v247, s[100:101] nt
	s_add_i32 m0, s99, 0x1000
	s_nop 0
	global_load_lds_dwordx4 v248, s[100:101] nt
	s_and_b64 vcc, exec, s[2:3]
	s_cbranch_vccnz .LBB0_971
	s_add_i32 s64, s85, s31
	s_lshl_b64 s[22:23], s[22:23], 9
	s_add_i32 m0, s64, 0x12000
	v_lshl_add_u64 v[66:67], v[156:157], 0, s[22:23]
	global_load_lds_dword v[66:67], off
	s_branch .LBB0_971
